# plus software-pipelined LayerNorm row loops (next row's loads in flight during the reductions, global ops, counted vmcnt) in all four LN phases
# baseline (speedup 1.0000x reference)
; __device__ __forceinline__ void ln_phase(float* io, const float* g, const float* b, bf16_t* hb, float* stats, int gw, int NGW, int lane) {
;     f32x4 gv[8], bv[8];
; #pragma unroll
;     for (int j = 0; j < 8; ++j) { gv[j] = *((const f32x4*)g + lane + 64 * j); bv[j] = *((const f32x4*)b + lane + 64 * j); }
;     for (int row = gw; row < M; row += NGW) {
;         f32x4* xr = (f32x4*)(io + (size_t)row * D) + lane;
;         f32x4 v[8]; float s = 0.f;
; #pragma unroll
;         for (int j = 0; j < 8; ++j) { v[j] = xr[64 * j]; s += (v[j][0] + v[j][1]) + (v[j][2] + v[j][3]); }
;         const float mean = wave_sum(s, lane) * (1.f / D); float s2 = 0.f;
.LBB0_273:
	s_or_b64 exec, exec, s[2:3]
	v_readlane_b32 s0, v254, 0
	s_waitcnt lgkmcnt(0)
	s_barrier
	v_mbcnt_lo_u32_b32 v0, -1, 0
	v_mbcnt_hi_u32_b32 v0, -1, v0
	s_add_i32 s8, 0, 0x23090
	v_or_b32_e32 v1, s0, v0
	s_add_i32 s9, 0, 0x23094
	v_readfirstlane_b32 s0, v1
	v_mov_b32_e32 v1, s8
	ds_read_b32 v1, v1
	v_mov_b32_e32 v2, s9
	s_add_i32 s1, 0, 0x23088
	ds_read_b32 v2, v2
	v_mov_b32_e32 v3, s1
	s_add_i32 s1, 0, 0x2308c
	ds_read_b32 v3, v3
	v_mov_b32_e32 v4, s1
	s_ashr_i32 s0, s0, 6
	ds_read_b32 v4, v4
	v_readlane_b32 s1, v254, 1
	s_add_i32 s2, s0, s1
	s_add_i32 s0, 0, 0x23018
	s_waitcnt lgkmcnt(0)
	v_readfirstlane_b32 s10, v1
	v_mov_b32_e32 v1, s0
	s_add_i32 s0, 0, 0x2301c
	v_readfirstlane_b32 s11, v2
	v_mov_b32_e32 v2, s0
	s_add_i32 s0, 0, 0x23020
	v_readfirstlane_b32 s6, v3
	v_mov_b32_e32 v3, s0
	s_add_i32 s0, 0, 0x23024
	v_readfirstlane_b32 s7, v4
	v_mov_b32_e32 v4, s0
	ds_read_b32 v1, v1
	ds_read_b32 v2, v2
	ds_read_b32 v3, v3
	ds_read_b32 v4, v4
	s_cmpk_gt_i32 s2, 0x7fff
	s_waitcnt lgkmcnt(0)
	v_readfirstlane_b32 s0, v1
	v_readfirstlane_b32 s1, v2
	v_readfirstlane_b32 s4, v3
	v_readfirstlane_b32 s5, v4
	s_cbranch_scc1 .LBB0_277
	v_and_b32_e32 v70, 63, v0
	v_lshlrev_b32_e32 v64, 4, v70
	v_mov_b32_e32 v65, 0
	v_lshl_add_u64 v[32:33], s[0:1], 0, v[64:65]
	s_movk_i32 s0, 0x1000
	v_add_co_u32_e32 v66, vcc, s0, v32
	v_lshl_add_u64 v[34:35], s[4:5], 0, v[64:65]
	s_nop 0
	v_addc_co_u32_e32 v67, vcc, 0, v33, vcc
	v_add_co_u32_e32 v68, vcc, s0, v34
	flat_load_dwordx4 v[0:3], v[32:33]
	flat_load_dwordx4 v[4:7], v[32:33] offset:1024
	flat_load_dwordx4 v[8:11], v[34:35]
	flat_load_dwordx4 v[12:15], v[34:35] offset:1024
	flat_load_dwordx4 v[16:19], v[32:33] offset:2048
	flat_load_dwordx4 v[20:23], v[32:33] offset:3072
	flat_load_dwordx4 v[24:27], v[34:35] offset:2048
	flat_load_dwordx4 v[28:31], v[34:35] offset:3072
	v_addc_co_u32_e32 v69, vcc, 0, v35, vcc
	flat_load_dwordx4 v[32:35], v[66:67]
	flat_load_dwordx4 v[36:39], v[66:67] offset:1024
	flat_load_dwordx4 v[40:43], v[68:69]
	flat_load_dwordx4 v[44:47], v[68:69] offset:1024
	flat_load_dwordx4 v[48:51], v[66:67] offset:2048
	flat_load_dwordx4 v[52:55], v[66:67] offset:3072
	flat_load_dwordx4 v[56:59], v[68:69] offset:2048
	flat_load_dwordx4 v[60:63], v[68:69] offset:3072
	s_ashr_i32 s3, s2, 31
	s_lshl_b64 s[0:1], s[2:3], 12
	v_lshlrev_b32_e32 v66, 2, v70
	s_add_u32 s0, s10, s0
	v_readlane_b32 s12, v254, 4
	v_xor_b32_e32 v90, 4, v66
	v_xor_b32_e32 v91, 8, v66
	v_xor_b32_e32 v92, 16, v66
	v_xor_b32_e32 v93, 32, v66
	v_xor_b32_e32 v94, 64, v66
	v_xor_b32_e32 v95, 0x80, v66
	v_lshlrev_b32_e32 v66, 3, v70
	v_mov_b32_e32 v67, v65
	s_addc_u32 s1, s11, s1
	v_readlane_b32 s13, v254, 5
	v_lshl_add_u64 v[66:67], s[0:1], 0, v[66:67]
	s_mov_b64 s[0:1], 0xf600000
	s_ashr_i32 s13, s12, 31
	v_lshl_add_u64 v[80:81], v[66:67], 0, s[0:1]
	s_lshl_b64 s[4:5], s[12:13], 12
	s_lshl_b64 s[0:1], s[2:3], 13
	s_add_u32 s0, s6, s0
	s_addc_u32 s1, s7, s1
	v_lshl_add_u64 v[64:65], s[0:1], 0, v[64:65]
	s_mov_b64 s[0:1], 0x1000
	v_lshl_add_u64 v[82:83], v[64:65], 0, s[0:1]
	s_lshl_b64 s[6:7], s[12:13], 13
	s_movk_i32 s3, 0xf800
	s_movk_i32 s10, 0xfc00
	v_mov_b32_e32 v96, 0x3727c5ac
	s_mov_b32 s11, 0xf800000
	v_mov_b32_e32 v97, 0x260
	v_add_co_u32_e32 v172, vcc, 0xfffff000, v82
	v_add_co_u32_e64 v174, s[0:1], s3, v82
	s_nop 0
	v_addc_co_u32_e32 v173, vcc, -1, v83, vcc
	v_add_co_u32_e32 v178, vcc, 0xfffff400, v82
	global_load_dwordx4 v[140:143], v[82:83], off
	v_addc_co_u32_e64 v175, s[0:1], -1, v83, s[0:1]
	global_load_dwordx4 v[144:147], v[82:83], off offset:1024
	global_load_dwordx4 v[148:151], v[82:83], off offset:2048
	global_load_dwordx4 v[152:155], v[82:83], off offset:3072
	global_load_dwordx4 v[156:159], v[172:173], off
	v_addc_co_u32_e32 v179, vcc, -1, v83, vcc
	v_add_co_u32_e64 v176, s[0:1], s10, v82
	global_load_dwordx4 v[160:163], v[174:175], off
	s_nop 0
	v_addc_co_u32_e64 v177, s[0:1], -1, v83, s[0:1]
	global_load_dwordx4 v[164:167], v[178:179], off
	global_load_dwordx4 v[168:171], v[176:177], off
	v_lshl_add_u64 v[82:83], v[82:83], 0, s[6:7]
	s_waitcnt vmcnt(0) lgkmcnt(0)
.LBB0_275:
	v_mov_b64_e32 v[64:65], v[140:141]
	v_mov_b64_e32 v[66:67], v[142:143]
	v_mov_b64_e32 v[68:69], v[144:145]
	v_mov_b64_e32 v[70:71], v[146:147]
	v_mov_b64_e32 v[72:73], v[148:149]
	v_mov_b64_e32 v[74:75], v[150:151]
	v_mov_b64_e32 v[76:77], v[152:153]
	v_mov_b64_e32 v[78:79], v[154:155]
	v_mov_b64_e32 v[102:103], v[156:157]
	v_mov_b64_e32 v[104:105], v[158:159]
	v_mov_b64_e32 v[98:99], v[160:161]
	v_mov_b64_e32 v[100:101], v[162:163]
	v_mov_b64_e32 v[106:107], v[164:165]
	v_mov_b64_e32 v[108:109], v[166:167]
	v_mov_b64_e32 v[86:87], v[168:169]
	v_mov_b64_e32 v[88:89], v[170:171]
	s_add_i32 s2, s2, s12
	s_cmp_lt_i32 s2, 0x8000
	s_cbranch_scc0 .Lln_skip0
	v_add_co_u32_e32 v172, vcc, 0xfffff000, v82
	v_add_co_u32_e64 v174, s[0:1], s3, v82
	s_nop 0
	v_addc_co_u32_e32 v173, vcc, -1, v83, vcc
	v_add_co_u32_e32 v178, vcc, 0xfffff400, v82
	global_load_dwordx4 v[140:143], v[82:83], off
	v_addc_co_u32_e64 v175, s[0:1], -1, v83, s[0:1]
	global_load_dwordx4 v[144:147], v[82:83], off offset:1024
	global_load_dwordx4 v[148:151], v[82:83], off offset:2048
	global_load_dwordx4 v[152:155], v[82:83], off offset:3072
	global_load_dwordx4 v[156:159], v[172:173], off
	v_addc_co_u32_e32 v179, vcc, -1, v83, vcc
	v_add_co_u32_e64 v176, s[0:1], s10, v82
	global_load_dwordx4 v[160:163], v[174:175], off
	s_nop 0
	v_addc_co_u32_e64 v177, s[0:1], -1, v83, s[0:1]
	global_load_dwordx4 v[164:167], v[178:179], off
	global_load_dwordx4 v[168:171], v[176:177], off
	v_lshl_add_u64 v[82:83], v[82:83], 0, s[6:7]
; __device__ __forceinline__ void ln_phase(float* io, const float* g, const float* b, bf16_t* hb, float* stats, int gw, int NGW, int lane) {
;     ...
;         f32x4 v[8]; float s = 0.f;
; #pragma unroll
;         for (int j = 0; j < 8; ++j) { v[j] = xr[64 * j]; s += (v[j][0] + v[j][1]) + (v[j][2] + v[j][3]); }
;         const float mean = wave_sum(s, lane) * (1.f / D); float s2 = 0.f;
; #pragma unroll
;         for (int j = 0; j < 8; ++j) { v[j] = v[j] - mean; s2 += (v[j][0] * v[j][0] + v[j][1] * v[j][1]) + (v[j][2] * v[j][2] + v[j][3] * v[j][3]); }
;         const float rstd = 1.0f / sqrtf(wave_sum(s2, lane) * (1.f / D) + 1e-5f);
.Lln_skip0:
	v_mov_b32_e32 v111, v66
	v_mov_b32_e32 v113, v67
	v_mov_b32_e32 v114, v69
	v_mov_b32_e32 v115, v70
	v_mov_b32_e32 v116, v68
	v_mov_b32_e32 v117, v71
	v_add_f32_e32 v118, v72, v73
	v_add_f32_e32 v120, v74, v75
	v_mov_b32_e32 v119, v78
	v_mov_b32_e32 v121, v79
	v_pk_add_f32 v[114:115], v[114:115], v[116:117]
	v_pk_add_f32 v[116:117], v[118:119], v[120:121]
	v_mov_b32_e32 v118, v102
	v_mov_b32_e32 v120, v103
	v_mov_b32_e32 v126, v104
	v_mov_b32_e32 v128, v105
	v_mov_b32_e32 v119, v106
	v_mov_b32_e32 v121, v107
	v_mov_b32_e32 v127, v108
	v_mov_b32_e32 v129, v109
	v_mov_b32_e32 v122, v99
	v_mov_b32_e32 v123, v100
	v_mov_b32_e32 v124, v98
	v_mov_b32_e32 v125, v101
	v_pk_add_f32 v[118:119], v[118:119], v[120:121]
	v_pk_add_f32 v[120:121], v[126:127], v[128:129]
	v_add_f32_e32 v110, v86, v87
	v_add_f32_e32 v112, v88, v89
	v_pk_add_f32 v[122:123], v[122:123], v[124:125]
	v_pk_add_f32 v[118:119], v[118:119], v[120:121]
	v_pk_add_f32 v[110:111], v[110:111], v[112:113]
	v_pk_add_f32 v[112:113], v[114:115], v[114:115] op_sel:[0,1] op_sel_hi:[1,0]
	v_pk_add_f32 v[114:115], v[122:123], v[122:123] op_sel:[0,1] op_sel_hi:[1,0]
	v_add_f32_e32 v84, 0, v118
	v_mov_b32_e32 v85, v64
	v_mov_b32_e32 v115, v65
	v_add_f32_e32 v84, v84, v119
	v_pk_add_f32 v[84:85], v[84:85], v[114:115]
	v_mov_b32_e32 v113, v77
	v_pk_add_f32 v[84:85], v[84:85], v[110:111]
	s_nop 0
	v_pk_add_f32 v[84:85], v[84:85], v[84:85] op_sel:[0,1] op_sel_hi:[1,0]
	s_nop 0
	v_mov_b32_e32 v85, v76
	v_pk_add_f32 v[84:85], v[84:85], v[112:113]
	s_nop 0
	v_pk_add_f32 v[84:85], v[84:85], v[116:117]
	s_nop 0
	v_add_f32_e32 v84, v84, v85
	ds_bpermute_b32 v85, v90, v84
	s_waitcnt lgkmcnt(0)
	v_add_f32_e32 v84, v84, v85
	ds_bpermute_b32 v85, v91, v84
	s_waitcnt lgkmcnt(0)
	v_add_f32_e32 v84, v84, v85
	ds_bpermute_b32 v85, v92, v84
	s_waitcnt lgkmcnt(0)
	v_add_f32_e32 v84, v84, v85
	ds_bpermute_b32 v85, v93, v84
	s_waitcnt lgkmcnt(0)
	v_add_f32_e32 v84, v84, v85
	ds_bpermute_b32 v85, v94, v84
	s_waitcnt lgkmcnt(0)
	v_add_f32_e32 v84, v84, v85
	ds_bpermute_b32 v85, v95, v84
	s_waitcnt lgkmcnt(0)
	v_add_f32_e32 v110, v84, v85
	v_fmamk_f32 v85, v110, 0xba000000, v105
	v_fmamk_f32 v103, v110, 0xba000000, v103
	v_fmamk_f32 v105, v110, 0xba000000, v109
	v_fmamk_f32 v107, v110, 0xba000000, v107
	v_fmamk_f32 v84, v110, 0xba000000, v104
	v_fmac_f32_e32 v102, 0xba000000, v110
	v_fmamk_f32 v104, v110, 0xba000000, v108
	v_fmac_f32_e32 v106, 0xba000000, v110
	v_fmamk_f32 v99, v110, 0xba000000, v99
	v_fmamk_f32 v98, v110, 0xba000000, v98
	v_fmamk_f32 v101, v110, 0xba000000, v101
	v_fmac_f32_e32 v100, 0xba000000, v110
	v_fmamk_f32 v87, v110, 0xba000000, v87
	v_fmamk_f32 v86, v110, 0xba000000, v86
	v_fmamk_f32 v89, v110, 0xba000000, v89
	v_fmac_f32_e32 v88, 0xba000000, v110
	v_fmamk_f32 v67, v110, 0xba000000, v67
	v_fmamk_f32 v66, v110, 0xba000000, v66
	v_fmamk_f32 v65, v110, 0xba000000, v65
	v_fmac_f32_e32 v64, 0xba000000, v110
	v_fmamk_f32 v69, v110, 0xba000000, v69
	v_fmamk_f32 v68, v110, 0xba000000, v68
	v_fmamk_f32 v71, v110, 0xba000000, v71
	v_fmac_f32_e32 v70, 0xba000000, v110
	v_fmamk_f32 v73, v110, 0xba000000, v73
	v_fmamk_f32 v72, v110, 0xba000000, v72
	v_fmamk_f32 v75, v110, 0xba000000, v75
	v_fmac_f32_e32 v74, 0xba000000, v110
	v_fmamk_f32 v79, v110, 0xba000000, v79
	v_fmamk_f32 v78, v110, 0xba000000, v78
	v_fmamk_f32 v77, v110, 0xba000000, v77
	v_fmac_f32_e32 v76, 0xba000000, v110
	v_mov_b32_e32 v110, v103
	v_mov_b32_e32 v111, v107
	v_mov_b32_e32 v114, v85
	v_mov_b32_e32 v115, v105
	v_mov_b32_e32 v108, v102
	v_mov_b32_e32 v109, v106
	v_mov_b32_e32 v112, v84
	v_mov_b32_e32 v113, v104
	v_pk_mul_f32 v[116:117], v[100:101], v[100:101]
	v_pk_mul_f32 v[118:119], v[98:99], v[98:99]
	v_pk_mul_f32 v[110:111], v[110:111], v[110:111]
	v_pk_mul_f32 v[114:115], v[114:115], v[114:115]
	v_pk_mov_b32 v[132:133], v[118:119], v[116:117] op_sel:[1,0]
	v_mov_b32_e32 v119, v117
	v_pk_fma_f32 v[108:109], v[108:109], v[108:109], v[110:111]
	v_pk_fma_f32 v[110:111], v[112:113], v[112:113], v[114:115]
	v_mul_f32_e32 v120, v86, v86
	v_mul_f32_e32 v122, v88, v88
	v_pk_add_f32 v[112:113], v[132:133], v[118:119]
	v_pk_add_f32 v[108:109], v[108:109], v[110:111]
	v_pk_fma_f32 v[116:117], v[86:87], v[86:87], v[120:121] op_sel_hi:[1,1,0]
	v_pk_fma_f32 v[120:121], v[88:89], v[88:89], v[122:123] op_sel_hi:[1,1,0]
	v_pk_add_f32 v[110:111], v[112:113], v[112:113] op_sel_hi:[0,1]
	v_pk_add_f32 v[108:109], v[108:109], v[108:109] op_sel_hi:[0,1]
	v_pk_mul_f32 v[124:125], v[70:71], v[70:71]
	v_pk_mul_f32 v[126:127], v[68:69], v[68:69]
	v_mul_f32_e32 v116, v64, v64
	v_mul_f32_e32 v120, v65, v65
	v_mul_f32_e32 v110, v66, v66
	v_mul_f32_e32 v108, v67, v67
	v_pk_mov_b32 v[122:123], v[126:127], v[124:125] op_sel:[1,0]
	v_mov_b32_e32 v127, v125
	v_pk_add_f32 v[112:113], v[116:117], v[120:121]
	v_pk_add_f32 v[108:109], v[110:111], v[108:109]
	v_mul_f32_e32 v128, v72, v72
	v_mul_f32_e32 v130, v74, v74
	v_pk_add_f32 v[114:115], v[122:123], v[126:127]
	v_pk_add_f32 v[108:109], v[112:113], v[108:109]
	v_pk_fma_f32 v[124:125], v[72:73], v[72:73], v[128:129] op_sel_hi:[1,1,0]
	v_pk_fma_f32 v[128:129], v[74:75], v[74:75], v[130:131] op_sel_hi:[1,1,0]
	v_pk_add_f32 v[114:115], v[114:115], v[114:115] op_sel_hi:[0,1]
	v_pk_add_f32 v[108:109], v[108:109], v[108:109] op_sel_hi:[0,1]
	v_mul_f32_e32 v124, v76, v76
	v_mul_f32_e32 v128, v77, v77
	v_mul_f32_e32 v114, v78, v78
	v_mul_f32_e32 v108, v79, v79
	v_pk_add_f32 v[116:117], v[124:125], v[128:129]
	v_pk_add_f32 v[108:109], v[114:115], v[108:109]
	s_nop 0
	v_pk_add_f32 v[108:109], v[116:117], v[108:109]
	s_nop 0
	v_add_f32_e32 v108, v108, v109
	ds_bpermute_b32 v109, v90, v108
	s_waitcnt lgkmcnt(0)
; __device__ __forceinline__ unsigned cvt_pk_bf16(float lo, float hi) { unsigned r; asm volatile("s_nop 1\n\tv_cvt_pk_bf16_f32 %0, %1, %2" : "=v"(r) : "v"(lo), "v"(hi)); return r; }
; __device__ __forceinline__ void ln_phase(float* io, const float* g, const float* b, bf16_t* hb, float* stats, int gw, int NGW, int lane) {
;     ...
;         const float rstd = 1.0f / sqrtf(wave_sum(s2, lane) * (1.f / D) + 1e-5f);
; #pragma unroll
;         for (int j = 0; j < 8; ++j) v[j] = v[j] * rstd * gv[j] + bv[j];
;         if (stats) {
;             u32x2* o8 = (u32x2*)(hb + (size_t)row * D) + lane;
; #pragma unroll
;             for (int j = 0; j < 8; ++j) { u32x2 w; w.x = cvt_pk_bf16(v[j][0], v[j][1]); w.y = cvt_pk_bf16(v[j][2], v[j][3]); o8[64 * j] = w; }
	v_add_f32_e32 v108, v108, v109
	ds_bpermute_b32 v109, v91, v108
	s_waitcnt lgkmcnt(0)
	v_add_f32_e32 v108, v108, v109
	ds_bpermute_b32 v109, v92, v108
	s_waitcnt lgkmcnt(0)
	v_add_f32_e32 v108, v108, v109
	ds_bpermute_b32 v109, v93, v108
	s_waitcnt lgkmcnt(0)
	v_add_f32_e32 v108, v108, v109
	ds_bpermute_b32 v109, v94, v108
	s_waitcnt lgkmcnt(0)
	v_add_f32_e32 v108, v108, v109
	ds_bpermute_b32 v109, v95, v108
	s_waitcnt lgkmcnt(0)
	v_add_f32_e32 v108, v108, v109
	v_fmamk_f32 v108, v108, 0x3a000000, v96
	v_mul_f32_e32 v109, 0x4f800000, v108
	v_cmp_gt_f32_e32 vcc, s11, v108
	s_nop 1
	v_cndmask_b32_e32 v108, v108, v109, vcc
	v_sqrt_f32_e32 v109, v108
	s_nop 0
	v_add_u32_e32 v110, -1, v109
	v_add_u32_e32 v111, 1, v109
	v_fma_f32 v112, -v110, v109, v108
	v_fma_f32 v113, -v111, v109, v108
	v_cmp_ge_f32_e64 s[0:1], 0, v112
	s_nop 1
	v_cndmask_b32_e64 v109, v109, v110, s[0:1]
	v_cmp_lt_f32_e64 s[0:1], 0, v113
	s_nop 1
	v_cndmask_b32_e64 v109, v109, v111, s[0:1]
	v_mul_f32_e32 v110, 0x37800000, v109
	v_cndmask_b32_e32 v109, v109, v110, vcc
	v_cmp_class_f32_e32 vcc, v108, v97
	s_nop 1
	v_cndmask_b32_e32 v108, v109, v108, vcc
	v_div_scale_f32 v109, s[0:1], v108, v108, 1.0
	v_rcp_f32_e32 v111, v109
	v_div_scale_f32 v110, vcc, 1.0, v108, 1.0
	v_fma_f32 v112, -v109, v111, 1.0
	v_fmac_f32_e32 v111, v112, v111
	v_mul_f32_e32 v112, v110, v111
	v_fma_f32 v113, -v109, v112, v110
	v_fmac_f32_e32 v112, v113, v111
	v_fma_f32 v109, -v109, v112, v110
	v_div_fmas_f32 v109, v109, v111, v112
	v_div_fixup_f32 v108, v109, v108, 1.0
	v_pk_mul_f32 v[84:85], v[84:85], v[108:109] op_sel_hi:[1,0]
	v_pk_mul_f32 v[102:103], v[102:103], v[108:109] op_sel_hi:[1,0]
	v_pk_mul_f32 v[104:105], v[104:105], v[108:109] op_sel_hi:[1,0]
	v_pk_mul_f32 v[106:107], v[106:107], v[108:109] op_sel_hi:[1,0]
	v_pk_fma_f32 v[102:103], v[0:1], v[102:103], v[8:9]
	v_pk_fma_f32 v[84:85], v[2:3], v[84:85], v[10:11]
	v_pk_mul_f32 v[100:101], v[100:101], v[108:109] op_sel_hi:[1,0]
	v_pk_mul_f32 v[98:99], v[98:99], v[108:109] op_sel_hi:[1,0]
	v_pk_mul_f32 v[64:65], v[64:65], v[108:109] op_sel_hi:[1,0]
	v_pk_fma_f32 v[106:107], v[4:5], v[106:107], v[12:13]
	v_pk_fma_f32 v[104:105], v[6:7], v[104:105], v[14:15]
	s_nop 1
	v_cvt_pk_bf16_f32 v102, v102, v103
	s_nop 1
	v_cvt_pk_bf16_f32 v103, v84, v85
	global_store_dwordx2 v[80:81], v[102:103], off
	s_nop 1
	v_cvt_pk_bf16_f32 v84, v106, v107
	s_nop 1
	v_cvt_pk_bf16_f32 v85, v104, v105
	v_pk_mul_f32 v[88:89], v[88:89], v[108:109] op_sel_hi:[1,0]
	v_pk_mul_f32 v[86:87], v[86:87], v[108:109] op_sel_hi:[1,0]
	v_pk_mul_f32 v[66:67], v[66:67], v[108:109] op_sel_hi:[1,0]
	v_pk_fma_f32 v[98:99], v[16:17], v[98:99], v[24:25]
	v_pk_fma_f32 v[100:101], v[18:19], v[100:101], v[26:27]
	v_pk_fma_f32 v[64:65], v[32:33], v[64:65], v[40:41]
	global_store_dwordx2 v[80:81], v[84:85], off offset:512
	s_nop 1
	v_cvt_pk_bf16_f32 v84, v98, v99
	s_nop 1
	v_cvt_pk_bf16_f32 v85, v100, v101
	v_pk_mul_f32 v[70:71], v[70:71], v[108:109] op_sel_hi:[1,0]
	v_pk_mul_f32 v[68:69], v[68:69], v[108:109] op_sel_hi:[1,0]
	v_pk_fma_f32 v[86:87], v[20:21], v[86:87], v[28:29]
	v_pk_fma_f32 v[88:89], v[22:23], v[88:89], v[30:31]
	v_pk_fma_f32 v[66:67], v[34:35], v[66:67], v[42:43]
	global_store_dwordx2 v[80:81], v[84:85], off offset:1024
	s_nop 1
	v_cvt_pk_bf16_f32 v84, v86, v87
	s_nop 1
	v_cvt_pk_bf16_f32 v85, v88, v89
	global_store_dwordx2 v[80:81], v[84:85], off offset:1536
	s_nop 1
	v_cvt_pk_bf16_f32 v64, v64, v65
	s_nop 1
	v_cvt_pk_bf16_f32 v65, v66, v67
	v_pk_mul_f32 v[74:75], v[74:75], v[108:109] op_sel_hi:[1,0]
	v_pk_mul_f32 v[72:73], v[72:73], v[108:109] op_sel_hi:[1,0]
	v_pk_fma_f32 v[68:69], v[36:37], v[68:69], v[44:45]
	v_pk_fma_f32 v[70:71], v[38:39], v[70:71], v[46:47]
	global_store_dwordx2 v[80:81], v[64:65], off offset:2048
	s_nop 1
	v_cvt_pk_bf16_f32 v64, v68, v69
	s_nop 1
	v_cvt_pk_bf16_f32 v65, v70, v71
	v_pk_mul_f32 v[78:79], v[78:79], v[108:109] op_sel_hi:[1,0]
	v_pk_mul_f32 v[76:77], v[76:77], v[108:109] op_sel_hi:[1,0]
	v_pk_fma_f32 v[72:73], v[48:49], v[72:73], v[56:57]
	v_pk_fma_f32 v[74:75], v[50:51], v[74:75], v[58:59]
	global_store_dwordx2 v[80:81], v[64:65], off offset:2560
	s_nop 1
	v_cvt_pk_bf16_f32 v64, v72, v73
	s_nop 1
	v_cvt_pk_bf16_f32 v65, v74, v75
	v_pk_fma_f32 v[76:77], v[52:53], v[76:77], v[60:61]
	v_pk_fma_f32 v[78:79], v[54:55], v[78:79], v[62:63]
	global_store_dwordx2 v[80:81], v[64:65], off offset:3072
	s_nop 1
	v_cvt_pk_bf16_f32 v64, v76, v77
	s_nop 1
	v_cvt_pk_bf16_f32 v65, v78, v79
	global_store_dwordx2 v[80:81], v[64:65], off offset:3584
	v_lshl_add_u64 v[80:81], v[80:81], 0, s[4:5]
	s_waitcnt vmcnt(8)
	s_cmp_lt_i32 s2, 0x8000
	s_cbranch_scc1 .LBB0_275
	v_writelane_b32 v254, s12, 4
	s_nop 1
	v_writelane_b32 v254, s13, 5

; __device__ __forceinline__ void ln_phase(float* io, const float* g, const float* b, bf16_t* hb, float* stats, int gw, int NGW, int lane) {
;     f32x4 gv[8], bv[8];
; #pragma unroll
;     for (int j = 0; j < 8; ++j) { gv[j] = *((const f32x4*)g + lane + 64 * j); bv[j] = *((const f32x4*)b + lane + 64 * j); }
;     for (int row = gw; row < M; row += NGW) {
;         f32x4* xr = (f32x4*)(io + (size_t)row * D) + lane;
;         f32x4 v[8]; float s = 0.f;
; #pragma unroll
;         for (int j = 0; j < 8; ++j) { v[j] = xr[64 * j]; s += (v[j][0] + v[j][1]) + (v[j][2] + v[j][3]); }
;         const float mean = wave_sum(s, lane) * (1.f / D); float s2 = 0.f;
.LBB0_832:
	s_or_b64 exec, exec, s[2:3]
	s_waitcnt lgkmcnt(0)
	s_barrier
	v_mbcnt_lo_u32_b32 v0, -1, 0
	v_mbcnt_hi_u32_b32 v0, -1, v0
	s_add_i32 s8, 0, 0x23090
	v_or_b32_e32 v1, s59, v0
	s_add_i32 s9, 0, 0x23094
	v_readfirstlane_b32 s0, v1
	v_mov_b32_e32 v1, s8
	ds_read_b32 v1, v1
	v_mov_b32_e32 v2, s9
	s_add_i32 s1, 0, 0x23088
	ds_read_b32 v2, v2
	v_mov_b32_e32 v3, s1
	s_add_i32 s1, 0, 0x2308c
	ds_read_b32 v3, v3
	v_mov_b32_e32 v4, s1
	s_ashr_i32 s0, s0, 6
	ds_read_b32 v4, v4
	v_readlane_b32 s1, v254, 1
	s_add_i32 s2, s0, s1
	s_add_i32 s0, 0, 0x23018
	s_waitcnt lgkmcnt(0)
	v_readfirstlane_b32 s10, v1
	v_mov_b32_e32 v1, s0
	s_add_i32 s0, 0, 0x2301c
	v_readfirstlane_b32 s11, v2
	v_mov_b32_e32 v2, s0
	s_add_i32 s0, 0, 0x23020
	v_readfirstlane_b32 s6, v3
	v_mov_b32_e32 v3, s0
	s_add_i32 s0, 0, 0x23024
	v_readfirstlane_b32 s7, v4
	v_mov_b32_e32 v4, s0
	ds_read_b32 v1, v1
	ds_read_b32 v2, v2
	ds_read_b32 v3, v3
	ds_read_b32 v4, v4
	s_cmpk_gt_i32 s2, 0x7fff
	s_waitcnt lgkmcnt(0)
	v_readfirstlane_b32 s4, v1
	v_readfirstlane_b32 s5, v2
	v_readfirstlane_b32 s0, v3
	v_readfirstlane_b32 s1, v4
	s_cbranch_scc1 .LBB0_836
	v_and_b32_e32 v70, 63, v0
	v_lshlrev_b32_e32 v64, 4, v70
	v_mov_b32_e32 v65, 0
	v_lshl_add_u64 v[32:33], s[4:5], 0, v[64:65]
	v_add_co_u32_e32 v0, vcc, 0x2000, v32
	v_lshl_add_u64 v[36:37], s[0:1], 0, v[64:65]
	s_nop 0
	v_addc_co_u32_e32 v1, vcc, 0, v33, vcc
	v_add_co_u32_e32 v40, vcc, 0x2000, v36
	s_mov_b64 s[4:5], 0x2000
	s_nop 0
	v_addc_co_u32_e32 v41, vcc, 0, v37, vcc
	v_add_co_u32_e32 v66, vcc, 0x3000, v32
	v_lshl_add_u64 v[34:35], v[32:33], 0, s[4:5]
	s_nop 0
	v_addc_co_u32_e32 v67, vcc, 0, v33, vcc
	v_lshl_add_u64 v[38:39], v[36:37], 0, s[4:5]
	v_add_co_u32_e32 v68, vcc, 0x3000, v36
	flat_load_dwordx4 v[0:3], v[0:1]
	s_nop 0
	flat_load_dwordx4 v[4:7], v[40:41]
	flat_load_dwordx4 v[8:11], v[34:35] offset:1024
	flat_load_dwordx4 v[12:15], v[34:35] offset:2048
	flat_load_dwordx4 v[16:19], v[38:39] offset:1024
	flat_load_dwordx4 v[20:23], v[38:39] offset:2048
	flat_load_dwordx4 v[24:27], v[34:35] offset:3072
	flat_load_dwordx4 v[28:31], v[38:39] offset:3072
	v_addc_co_u32_e32 v69, vcc, 0, v37, vcc
	flat_load_dwordx4 v[32:35], v[66:67]
	flat_load_dwordx4 v[36:39], v[66:67] offset:1024
	flat_load_dwordx4 v[40:43], v[68:69]
	flat_load_dwordx4 v[44:47], v[68:69] offset:1024
	flat_load_dwordx4 v[48:51], v[66:67] offset:2048
	flat_load_dwordx4 v[52:55], v[66:67] offset:3072
	flat_load_dwordx4 v[56:59], v[68:69] offset:2048
	flat_load_dwordx4 v[60:63], v[68:69] offset:3072
	s_ashr_i32 s3, s2, 31
	s_lshl_b64 s[0:1], s[2:3], 12
	v_lshlrev_b32_e32 v66, 2, v70
	s_add_u32 s0, s10, s0
	v_xor_b32_e32 v90, 4, v66
	v_xor_b32_e32 v91, 8, v66
	v_xor_b32_e32 v92, 16, v66
	v_xor_b32_e32 v93, 32, v66
	v_xor_b32_e32 v94, 64, v66
	v_xor_b32_e32 v95, 0x80, v66
	v_lshlrev_b32_e32 v66, 3, v70
	v_mov_b32_e32 v67, v65
	s_addc_u32 s1, s11, s1
	v_lshl_add_u64 v[66:67], s[0:1], 0, v[66:67]
	s_mov_b64 s[0:1], 0xf600000
	s_ashr_i32 s59, s58, 31
	v_lshl_add_u64 v[80:81], v[66:67], 0, s[0:1]
	s_lshl_b64 s[4:5], s[58:59], 12
	s_lshl_b64 s[0:1], s[2:3], 13
	s_add_u32 s0, s6, s0
	s_addc_u32 s1, s7, s1
	v_lshl_add_u64 v[64:65], s[0:1], 0, v[64:65]
	s_mov_b64 s[0:1], 0x1000
	v_lshl_add_u64 v[82:83], v[64:65], 0, s[0:1]
	s_lshl_b64 s[6:7], s[58:59], 13
	s_movk_i32 s3, 0xf800
	s_movk_i32 s10, 0xfc00
	v_mov_b32_e32 v96, 0x3727c5ac
	s_mov_b32 s11, 0xf800000
	v_mov_b32_e32 v97, 0x260
	v_add_co_u32_e32 v172, vcc, 0xfffff000, v82
	v_add_co_u32_e64 v174, s[0:1], s3, v82
	s_nop 0
	v_addc_co_u32_e32 v173, vcc, -1, v83, vcc
	v_add_co_u32_e32 v178, vcc, 0xfffff400, v82
	global_load_dwordx4 v[140:143], v[82:83], off
	v_addc_co_u32_e64 v175, s[0:1], -1, v83, s[0:1]
	global_load_dwordx4 v[144:147], v[82:83], off offset:1024
	global_load_dwordx4 v[148:151], v[82:83], off offset:2048
	global_load_dwordx4 v[152:155], v[82:83], off offset:3072
	global_load_dwordx4 v[156:159], v[172:173], off
	v_addc_co_u32_e32 v179, vcc, -1, v83, vcc
	v_add_co_u32_e64 v176, s[0:1], s10, v82
	global_load_dwordx4 v[160:163], v[174:175], off
	s_nop 0
	v_addc_co_u32_e64 v177, s[0:1], -1, v83, s[0:1]
	global_load_dwordx4 v[164:167], v[178:179], off
	global_load_dwordx4 v[168:171], v[176:177], off
	v_lshl_add_u64 v[82:83], v[82:83], 0, s[6:7]
	s_waitcnt vmcnt(0) lgkmcnt(0)
.LBB0_834:
	v_mov_b64_e32 v[64:65], v[140:141]
	v_mov_b64_e32 v[66:67], v[142:143]
	v_mov_b64_e32 v[68:69], v[144:145]
	v_mov_b64_e32 v[70:71], v[146:147]
	v_mov_b64_e32 v[72:73], v[148:149]
	v_mov_b64_e32 v[74:75], v[150:151]
	v_mov_b64_e32 v[76:77], v[152:153]
	v_mov_b64_e32 v[78:79], v[154:155]
	v_mov_b64_e32 v[102:103], v[156:157]
	v_mov_b64_e32 v[104:105], v[158:159]
	v_mov_b64_e32 v[98:99], v[160:161]
	v_mov_b64_e32 v[100:101], v[162:163]
	v_mov_b64_e32 v[106:107], v[164:165]
	v_mov_b64_e32 v[108:109], v[166:167]
	v_mov_b64_e32 v[86:87], v[168:169]
	v_mov_b64_e32 v[88:89], v[170:171]
	s_add_i32 s2, s2, s58
	s_cmp_lt_i32 s2, 0x8000
	s_cbranch_scc0 .Lln_skip1
	v_add_co_u32_e32 v172, vcc, 0xfffff000, v82
	v_add_co_u32_e64 v174, s[0:1], s3, v82
	s_nop 0
	v_addc_co_u32_e32 v173, vcc, -1, v83, vcc
	v_add_co_u32_e32 v178, vcc, 0xfffff400, v82
	global_load_dwordx4 v[140:143], v[82:83], off
	v_addc_co_u32_e64 v175, s[0:1], -1, v83, s[0:1]
	global_load_dwordx4 v[144:147], v[82:83], off offset:1024
	global_load_dwordx4 v[148:151], v[82:83], off offset:2048
	global_load_dwordx4 v[152:155], v[82:83], off offset:3072
	global_load_dwordx4 v[156:159], v[172:173], off
	v_addc_co_u32_e32 v179, vcc, -1, v83, vcc
	v_add_co_u32_e64 v176, s[0:1], s10, v82
	global_load_dwordx4 v[160:163], v[174:175], off
	s_nop 0
	v_addc_co_u32_e64 v177, s[0:1], -1, v83, s[0:1]
	global_load_dwordx4 v[164:167], v[178:179], off
	global_load_dwordx4 v[168:171], v[176:177], off
	v_lshl_add_u64 v[82:83], v[82:83], 0, s[6:7]
; __device__ __forceinline__ void ln_phase(float* io, const float* g, const float* b, bf16_t* hb, float* stats, int gw, int NGW, int lane) {
;     ...
;         f32x4 v[8]; float s = 0.f;
; #pragma unroll
;         for (int j = 0; j < 8; ++j) { v[j] = xr[64 * j]; s += (v[j][0] + v[j][1]) + (v[j][2] + v[j][3]); }
;         const float mean = wave_sum(s, lane) * (1.f / D); float s2 = 0.f;
; #pragma unroll
;         for (int j = 0; j < 8; ++j) { v[j] = v[j] - mean; s2 += (v[j][0] * v[j][0] + v[j][1] * v[j][1]) + (v[j][2] * v[j][2] + v[j][3] * v[j][3]); }
;         const float rstd = 1.0f / sqrtf(wave_sum(s2, lane) * (1.f / D) + 1e-5f);
.Lln_skip1:
	v_mov_b32_e32 v111, v66
	v_mov_b32_e32 v113, v67
	v_mov_b32_e32 v114, v69
	v_mov_b32_e32 v115, v70
	v_mov_b32_e32 v116, v68
	v_mov_b32_e32 v117, v71
	v_add_f32_e32 v118, v72, v73
	v_add_f32_e32 v120, v74, v75
	v_mov_b32_e32 v119, v78
	v_mov_b32_e32 v121, v79
	v_pk_add_f32 v[114:115], v[114:115], v[116:117]
	v_pk_add_f32 v[116:117], v[118:119], v[120:121]
	v_mov_b32_e32 v118, v102
	v_mov_b32_e32 v120, v103
	v_mov_b32_e32 v126, v104
	v_mov_b32_e32 v128, v105
	v_mov_b32_e32 v119, v106
	v_mov_b32_e32 v121, v107
	v_mov_b32_e32 v127, v108
	v_mov_b32_e32 v129, v109
	v_mov_b32_e32 v122, v99
	v_mov_b32_e32 v123, v100
	v_mov_b32_e32 v124, v98
	v_mov_b32_e32 v125, v101
	v_pk_add_f32 v[118:119], v[118:119], v[120:121]
	v_pk_add_f32 v[120:121], v[126:127], v[128:129]
	v_add_f32_e32 v110, v86, v87
	v_add_f32_e32 v112, v88, v89
	v_pk_add_f32 v[122:123], v[122:123], v[124:125]
	v_pk_add_f32 v[118:119], v[118:119], v[120:121]
	v_pk_add_f32 v[110:111], v[110:111], v[112:113]
	v_pk_add_f32 v[112:113], v[114:115], v[114:115] op_sel:[0,1] op_sel_hi:[1,0]
	v_pk_add_f32 v[114:115], v[122:123], v[122:123] op_sel:[0,1] op_sel_hi:[1,0]
	v_add_f32_e32 v84, 0, v118
	v_mov_b32_e32 v85, v64
	v_mov_b32_e32 v115, v65
	v_add_f32_e32 v84, v84, v119
	v_pk_add_f32 v[84:85], v[84:85], v[114:115]
	v_mov_b32_e32 v113, v77
	v_pk_add_f32 v[84:85], v[84:85], v[110:111]
	s_nop 0
	v_pk_add_f32 v[84:85], v[84:85], v[84:85] op_sel:[0,1] op_sel_hi:[1,0]
	s_nop 0
	v_mov_b32_e32 v85, v76
	v_pk_add_f32 v[84:85], v[84:85], v[112:113]
	s_nop 0
	v_pk_add_f32 v[84:85], v[84:85], v[116:117]
	s_nop 0
	v_add_f32_e32 v84, v84, v85
	ds_bpermute_b32 v85, v90, v84
	s_waitcnt lgkmcnt(0)
	v_add_f32_e32 v84, v84, v85
	ds_bpermute_b32 v85, v91, v84
	s_waitcnt lgkmcnt(0)
	v_add_f32_e32 v84, v84, v85
	ds_bpermute_b32 v85, v92, v84
	s_waitcnt lgkmcnt(0)
	v_add_f32_e32 v84, v84, v85
	ds_bpermute_b32 v85, v93, v84
	s_waitcnt lgkmcnt(0)
	v_add_f32_e32 v84, v84, v85
	ds_bpermute_b32 v85, v94, v84
	s_waitcnt lgkmcnt(0)
	v_add_f32_e32 v84, v84, v85
	ds_bpermute_b32 v85, v95, v84
	s_waitcnt lgkmcnt(0)
	v_add_f32_e32 v110, v84, v85
	v_fmamk_f32 v85, v110, 0xba000000, v105
	v_fmamk_f32 v103, v110, 0xba000000, v103
	v_fmamk_f32 v105, v110, 0xba000000, v109
	v_fmamk_f32 v107, v110, 0xba000000, v107
	v_fmamk_f32 v84, v110, 0xba000000, v104
	v_fmac_f32_e32 v102, 0xba000000, v110
	v_fmamk_f32 v104, v110, 0xba000000, v108
	v_fmac_f32_e32 v106, 0xba000000, v110
	v_fmamk_f32 v99, v110, 0xba000000, v99
	v_fmamk_f32 v98, v110, 0xba000000, v98
	v_fmamk_f32 v101, v110, 0xba000000, v101
	v_fmac_f32_e32 v100, 0xba000000, v110
	v_fmamk_f32 v87, v110, 0xba000000, v87
	v_fmamk_f32 v86, v110, 0xba000000, v86
	v_fmamk_f32 v89, v110, 0xba000000, v89
	v_fmac_f32_e32 v88, 0xba000000, v110
	v_fmamk_f32 v67, v110, 0xba000000, v67
	v_fmamk_f32 v66, v110, 0xba000000, v66
	v_fmamk_f32 v65, v110, 0xba000000, v65
	v_fmac_f32_e32 v64, 0xba000000, v110
	v_fmamk_f32 v69, v110, 0xba000000, v69
	v_fmamk_f32 v68, v110, 0xba000000, v68
	v_fmamk_f32 v71, v110, 0xba000000, v71
	v_fmac_f32_e32 v70, 0xba000000, v110
	v_fmamk_f32 v73, v110, 0xba000000, v73
	v_fmamk_f32 v72, v110, 0xba000000, v72
	v_fmamk_f32 v75, v110, 0xba000000, v75
	v_fmac_f32_e32 v74, 0xba000000, v110
	v_fmamk_f32 v79, v110, 0xba000000, v79
	v_fmamk_f32 v78, v110, 0xba000000, v78
	v_fmamk_f32 v77, v110, 0xba000000, v77
	v_fmac_f32_e32 v76, 0xba000000, v110
	v_mov_b32_e32 v110, v103
	v_mov_b32_e32 v111, v107
	v_mov_b32_e32 v114, v85
	v_mov_b32_e32 v115, v105
	v_mov_b32_e32 v108, v102
	v_mov_b32_e32 v109, v106
	v_mov_b32_e32 v112, v84
	v_mov_b32_e32 v113, v104
	v_pk_mul_f32 v[116:117], v[100:101], v[100:101]
	v_pk_mul_f32 v[118:119], v[98:99], v[98:99]
	v_pk_mul_f32 v[110:111], v[110:111], v[110:111]
	v_pk_mul_f32 v[114:115], v[114:115], v[114:115]
	v_pk_mov_b32 v[132:133], v[118:119], v[116:117] op_sel:[1,0]
	v_mov_b32_e32 v119, v117
	v_pk_fma_f32 v[108:109], v[108:109], v[108:109], v[110:111]
	v_pk_fma_f32 v[110:111], v[112:113], v[112:113], v[114:115]
	v_mul_f32_e32 v120, v86, v86
	v_mul_f32_e32 v122, v88, v88
	v_pk_add_f32 v[112:113], v[132:133], v[118:119]
	v_pk_add_f32 v[108:109], v[108:109], v[110:111]
	v_pk_fma_f32 v[116:117], v[86:87], v[86:87], v[120:121] op_sel_hi:[1,1,0]
	v_pk_fma_f32 v[120:121], v[88:89], v[88:89], v[122:123] op_sel_hi:[1,1,0]
	v_pk_add_f32 v[110:111], v[112:113], v[112:113] op_sel_hi:[0,1]
	v_pk_add_f32 v[108:109], v[108:109], v[108:109] op_sel_hi:[0,1]
	v_pk_mul_f32 v[124:125], v[70:71], v[70:71]
	v_pk_mul_f32 v[126:127], v[68:69], v[68:69]
	v_mul_f32_e32 v116, v64, v64
	v_mul_f32_e32 v120, v65, v65
	v_mul_f32_e32 v110, v66, v66
	v_mul_f32_e32 v108, v67, v67
	v_pk_mov_b32 v[122:123], v[126:127], v[124:125] op_sel:[1,0]
	v_mov_b32_e32 v127, v125
	v_pk_add_f32 v[112:113], v[116:117], v[120:121]
	v_pk_add_f32 v[108:109], v[110:111], v[108:109]
	v_mul_f32_e32 v128, v72, v72
	v_mul_f32_e32 v130, v74, v74
	v_pk_add_f32 v[114:115], v[122:123], v[126:127]
	v_pk_add_f32 v[108:109], v[112:113], v[108:109]
	v_pk_fma_f32 v[124:125], v[72:73], v[72:73], v[128:129] op_sel_hi:[1,1,0]
	v_pk_fma_f32 v[128:129], v[74:75], v[74:75], v[130:131] op_sel_hi:[1,1,0]
	v_pk_add_f32 v[114:115], v[114:115], v[114:115] op_sel_hi:[0,1]
	v_pk_add_f32 v[108:109], v[108:109], v[108:109] op_sel_hi:[0,1]
	v_mul_f32_e32 v124, v76, v76
	v_mul_f32_e32 v128, v77, v77
	v_mul_f32_e32 v114, v78, v78
	v_mul_f32_e32 v108, v79, v79
	v_pk_add_f32 v[116:117], v[124:125], v[128:129]
	v_pk_add_f32 v[108:109], v[114:115], v[108:109]
	s_nop 0
	v_pk_add_f32 v[108:109], v[116:117], v[108:109]
	s_nop 0
	v_add_f32_e32 v108, v108, v109
	ds_bpermute_b32 v109, v90, v108
	s_waitcnt lgkmcnt(0)
; __device__ __forceinline__ unsigned cvt_pk_bf16(float lo, float hi) { unsigned r; asm volatile("s_nop 1\n\tv_cvt_pk_bf16_f32 %0, %1, %2" : "=v"(r) : "v"(lo), "v"(hi)); return r; }
; __device__ __forceinline__ void ln_phase(float* io, const float* g, const float* b, bf16_t* hb, float* stats, int gw, int NGW, int lane) {
;     ...
;         const float rstd = 1.0f / sqrtf(wave_sum(s2, lane) * (1.f / D) + 1e-5f);
; #pragma unroll
;         for (int j = 0; j < 8; ++j) v[j] = v[j] * rstd * gv[j] + bv[j];
;         if (stats) {
;             u32x2* o8 = (u32x2*)(hb + (size_t)row * D) + lane;
; #pragma unroll
;             for (int j = 0; j < 8; ++j) { u32x2 w; w.x = cvt_pk_bf16(v[j][0], v[j][1]); w.y = cvt_pk_bf16(v[j][2], v[j][3]); o8[64 * j] = w; }
	v_add_f32_e32 v108, v108, v109
	ds_bpermute_b32 v109, v91, v108
	s_waitcnt lgkmcnt(0)
	v_add_f32_e32 v108, v108, v109
	ds_bpermute_b32 v109, v92, v108
	s_waitcnt lgkmcnt(0)
	v_add_f32_e32 v108, v108, v109
	ds_bpermute_b32 v109, v93, v108
	s_waitcnt lgkmcnt(0)
	v_add_f32_e32 v108, v108, v109
	ds_bpermute_b32 v109, v94, v108
	s_waitcnt lgkmcnt(0)
	v_add_f32_e32 v108, v108, v109
	ds_bpermute_b32 v109, v95, v108
	s_waitcnt lgkmcnt(0)
	v_add_f32_e32 v108, v108, v109
	v_fmamk_f32 v108, v108, 0x3a000000, v96
	v_mul_f32_e32 v109, 0x4f800000, v108
	v_cmp_gt_f32_e32 vcc, s11, v108
	s_nop 1
	v_cndmask_b32_e32 v108, v108, v109, vcc
	v_sqrt_f32_e32 v109, v108
	s_nop 0
	v_add_u32_e32 v110, -1, v109
	v_add_u32_e32 v111, 1, v109
	v_fma_f32 v112, -v110, v109, v108
	v_fma_f32 v113, -v111, v109, v108
	v_cmp_ge_f32_e64 s[0:1], 0, v112
	s_nop 1
	v_cndmask_b32_e64 v109, v109, v110, s[0:1]
	v_cmp_lt_f32_e64 s[0:1], 0, v113
	s_nop 1
	v_cndmask_b32_e64 v109, v109, v111, s[0:1]
	v_mul_f32_e32 v110, 0x37800000, v109
	v_cndmask_b32_e32 v109, v109, v110, vcc
	v_cmp_class_f32_e32 vcc, v108, v97
	s_nop 1
	v_cndmask_b32_e32 v108, v109, v108, vcc
	v_div_scale_f32 v109, s[0:1], v108, v108, 1.0
	v_rcp_f32_e32 v111, v109
	v_div_scale_f32 v110, vcc, 1.0, v108, 1.0
	v_fma_f32 v112, -v109, v111, 1.0
	v_fmac_f32_e32 v111, v112, v111
	v_mul_f32_e32 v112, v110, v111
	v_fma_f32 v113, -v109, v112, v110
	v_fmac_f32_e32 v112, v113, v111
	v_fma_f32 v109, -v109, v112, v110
	v_div_fmas_f32 v109, v109, v111, v112
	v_div_fixup_f32 v108, v109, v108, 1.0
	v_pk_mul_f32 v[84:85], v[84:85], v[108:109] op_sel_hi:[1,0]
	v_pk_mul_f32 v[102:103], v[102:103], v[108:109] op_sel_hi:[1,0]
	v_pk_mul_f32 v[104:105], v[104:105], v[108:109] op_sel_hi:[1,0]
	v_pk_mul_f32 v[106:107], v[106:107], v[108:109] op_sel_hi:[1,0]
	v_pk_fma_f32 v[102:103], v[0:1], v[102:103], v[4:5]
	v_pk_fma_f32 v[84:85], v[2:3], v[84:85], v[6:7]
	v_pk_mul_f32 v[100:101], v[100:101], v[108:109] op_sel_hi:[1,0]
	v_pk_mul_f32 v[98:99], v[98:99], v[108:109] op_sel_hi:[1,0]
	v_pk_mul_f32 v[64:65], v[64:65], v[108:109] op_sel_hi:[1,0]
	v_pk_fma_f32 v[106:107], v[8:9], v[106:107], v[16:17]
	v_pk_fma_f32 v[104:105], v[10:11], v[104:105], v[18:19]
	s_nop 1
	v_cvt_pk_bf16_f32 v102, v102, v103
	s_nop 1
	v_cvt_pk_bf16_f32 v103, v84, v85
	global_store_dwordx2 v[80:81], v[102:103], off
	s_nop 1
	v_cvt_pk_bf16_f32 v84, v106, v107
	s_nop 1
	v_cvt_pk_bf16_f32 v85, v104, v105
	v_pk_mul_f32 v[88:89], v[88:89], v[108:109] op_sel_hi:[1,0]
	v_pk_mul_f32 v[86:87], v[86:87], v[108:109] op_sel_hi:[1,0]
	v_pk_mul_f32 v[66:67], v[66:67], v[108:109] op_sel_hi:[1,0]
	v_pk_fma_f32 v[98:99], v[12:13], v[98:99], v[20:21]
	v_pk_fma_f32 v[100:101], v[14:15], v[100:101], v[22:23]
	v_pk_fma_f32 v[64:65], v[32:33], v[64:65], v[40:41]
	global_store_dwordx2 v[80:81], v[84:85], off offset:512
	s_nop 1
	v_cvt_pk_bf16_f32 v84, v98, v99
	s_nop 1
	v_cvt_pk_bf16_f32 v85, v100, v101
	v_pk_mul_f32 v[70:71], v[70:71], v[108:109] op_sel_hi:[1,0]
	v_pk_mul_f32 v[68:69], v[68:69], v[108:109] op_sel_hi:[1,0]
	v_pk_fma_f32 v[86:87], v[24:25], v[86:87], v[28:29]
	v_pk_fma_f32 v[88:89], v[26:27], v[88:89], v[30:31]
	v_pk_fma_f32 v[66:67], v[34:35], v[66:67], v[42:43]
	global_store_dwordx2 v[80:81], v[84:85], off offset:1024
	s_nop 1
	v_cvt_pk_bf16_f32 v84, v86, v87
	s_nop 1
	v_cvt_pk_bf16_f32 v85, v88, v89
	global_store_dwordx2 v[80:81], v[84:85], off offset:1536
	s_nop 1
	v_cvt_pk_bf16_f32 v64, v64, v65
	s_nop 1
	v_cvt_pk_bf16_f32 v65, v66, v67
	v_pk_mul_f32 v[74:75], v[74:75], v[108:109] op_sel_hi:[1,0]
	v_pk_mul_f32 v[72:73], v[72:73], v[108:109] op_sel_hi:[1,0]
	v_pk_fma_f32 v[68:69], v[36:37], v[68:69], v[44:45]
	v_pk_fma_f32 v[70:71], v[38:39], v[70:71], v[46:47]
	global_store_dwordx2 v[80:81], v[64:65], off offset:2048
	s_nop 1
	v_cvt_pk_bf16_f32 v64, v68, v69
	s_nop 1
	v_cvt_pk_bf16_f32 v65, v70, v71
	v_pk_mul_f32 v[78:79], v[78:79], v[108:109] op_sel_hi:[1,0]
	v_pk_mul_f32 v[76:77], v[76:77], v[108:109] op_sel_hi:[1,0]
	v_pk_fma_f32 v[72:73], v[48:49], v[72:73], v[56:57]
	v_pk_fma_f32 v[74:75], v[50:51], v[74:75], v[58:59]
	global_store_dwordx2 v[80:81], v[64:65], off offset:2560
	s_nop 1
	v_cvt_pk_bf16_f32 v64, v72, v73
	s_nop 1
	v_cvt_pk_bf16_f32 v65, v74, v75
	v_pk_fma_f32 v[76:77], v[52:53], v[76:77], v[60:61]
	v_pk_fma_f32 v[78:79], v[54:55], v[78:79], v[62:63]
	global_store_dwordx2 v[80:81], v[64:65], off offset:3072
	s_nop 1
	v_cvt_pk_bf16_f32 v64, v76, v77
	s_nop 1
	v_cvt_pk_bf16_f32 v65, v78, v79
	global_store_dwordx2 v[80:81], v[64:65], off offset:3584
	v_lshl_add_u64 v[80:81], v[80:81], 0, s[4:5]
	s_waitcnt vmcnt(8)
	s_cmp_lt_i32 s2, 0x8000
	s_cbranch_scc1 .LBB0_834
	v_readlane_b32 s59, v254, 0

; __device__ __forceinline__ void ln_phase(float* io, const float* g, const float* b, bf16_t* hb, float* stats, int gw, int NGW, int lane) {
;     f32x4 gv[8], bv[8];
; #pragma unroll
;     for (int j = 0; j < 8; ++j) { gv[j] = *((const f32x4*)g + lane + 64 * j); bv[j] = *((const f32x4*)b + lane + 64 * j); }
;     for (int row = gw; row < M; row += NGW) {
;         f32x4* xr = (f32x4*)(io + (size_t)row * D) + lane;
;         f32x4 v[8]; float s = 0.f;
; #pragma unroll
;         for (int j = 0; j < 8; ++j) { v[j] = xr[64 * j]; s += (v[j][0] + v[j][1]) + (v[j][2] + v[j][3]); }
;         const float mean = wave_sum(s, lane) * (1.f / D); float s2 = 0.f;
.LBB0_1034:
	v_mbcnt_lo_u32_b32 v0, -1, 0
	v_mbcnt_hi_u32_b32 v0, -1, v0
	v_mov_b32_e32 v2, s49
	v_or_b32_e32 v1, s59, v0
	s_add_i32 s1, 0, 0x23088
	v_readfirstlane_b32 s0, v1
	v_mov_b32_e32 v1, s48
	ds_read_b32 v1, v1
	ds_read_b32 v2, v2
	v_mov_b32_e32 v3, s1
	s_add_i32 s1, 0, 0x2308c
	ds_read_b32 v3, v3
	v_mov_b32_e32 v4, s1
	s_ashr_i32 s0, s0, 6
	ds_read_b32 v4, v4
	v_readlane_b32 s1, v254, 1
	s_add_i32 s2, s0, s1
	s_add_i32 s0, 0, 0x23018
	s_waitcnt lgkmcnt(0)
	v_readfirstlane_b32 s8, v1
	v_mov_b32_e32 v1, s0
	s_add_i32 s0, 0, 0x2301c
	v_readfirstlane_b32 s9, v2
	v_mov_b32_e32 v2, s0
	s_add_i32 s0, 0, 0x23020
	v_readfirstlane_b32 s6, v3
	v_mov_b32_e32 v3, s0
	s_add_i32 s0, 0, 0x23024
	v_readfirstlane_b32 s7, v4
	v_mov_b32_e32 v4, s0
	ds_read_b32 v1, v1
	ds_read_b32 v2, v2
	ds_read_b32 v3, v3
	ds_read_b32 v4, v4
	s_cmpk_gt_i32 s2, 0x7fff
	s_waitcnt lgkmcnt(0)
	v_readfirstlane_b32 s4, v1
	v_readfirstlane_b32 s5, v2
	v_readfirstlane_b32 s0, v3
	v_readfirstlane_b32 s1, v4
	s_cbranch_scc1 .LBB0_1038
	v_and_b32_e32 v70, 63, v0
	v_lshlrev_b32_e32 v64, 4, v70
	v_mov_b32_e32 v65, 0
	v_lshl_add_u64 v[32:33], s[4:5], 0, v[64:65]
	v_add_co_u32_e32 v0, vcc, 0x4000, v32
	v_lshl_add_u64 v[36:37], s[0:1], 0, v[64:65]
	s_nop 0
	v_addc_co_u32_e32 v1, vcc, 0, v33, vcc
	v_add_co_u32_e32 v40, vcc, 0x4000, v36
	s_mov_b64 s[4:5], 0x4000
	s_nop 0
	v_addc_co_u32_e32 v41, vcc, 0, v37, vcc
	v_add_co_u32_e32 v66, vcc, 0x5000, v32
	v_lshl_add_u64 v[34:35], v[32:33], 0, s[4:5]
	s_nop 0
	v_addc_co_u32_e32 v67, vcc, 0, v33, vcc
	v_lshl_add_u64 v[38:39], v[36:37], 0, s[4:5]
	v_add_co_u32_e32 v68, vcc, 0x5000, v36
	flat_load_dwordx4 v[0:3], v[0:1]
	s_nop 0
	flat_load_dwordx4 v[4:7], v[40:41]
	flat_load_dwordx4 v[8:11], v[34:35] offset:1024
	flat_load_dwordx4 v[12:15], v[34:35] offset:2048
	flat_load_dwordx4 v[16:19], v[38:39] offset:1024
	flat_load_dwordx4 v[20:23], v[38:39] offset:2048
	flat_load_dwordx4 v[24:27], v[34:35] offset:3072
	flat_load_dwordx4 v[28:31], v[38:39] offset:3072
	v_addc_co_u32_e32 v69, vcc, 0, v37, vcc
	flat_load_dwordx4 v[32:35], v[66:67]
	flat_load_dwordx4 v[36:39], v[66:67] offset:1024
	flat_load_dwordx4 v[40:43], v[68:69]
	flat_load_dwordx4 v[44:47], v[68:69] offset:1024
	flat_load_dwordx4 v[48:51], v[66:67] offset:2048
	flat_load_dwordx4 v[52:55], v[66:67] offset:3072
	flat_load_dwordx4 v[56:59], v[68:69] offset:2048
	flat_load_dwordx4 v[60:63], v[68:69] offset:3072
	s_ashr_i32 s3, s2, 31
	s_lshl_b64 s[0:1], s[2:3], 12
	v_lshlrev_b32_e32 v66, 2, v70
	s_add_u32 s0, s8, s0
	v_xor_b32_e32 v90, 4, v66
	v_xor_b32_e32 v91, 8, v66
	v_xor_b32_e32 v92, 16, v66
	v_xor_b32_e32 v93, 32, v66
	v_xor_b32_e32 v94, 64, v66
	v_xor_b32_e32 v95, 0x80, v66
	v_lshlrev_b32_e32 v66, 3, v70
	v_mov_b32_e32 v67, v65
	s_addc_u32 s1, s9, s1
	v_lshl_add_u64 v[66:67], s[0:1], 0, v[66:67]
	s_mov_b64 s[0:1], 0xf600000
	s_ashr_i32 s59, s58, 31
	v_lshl_add_u64 v[80:81], v[66:67], 0, s[0:1]
	s_lshl_b64 s[4:5], s[58:59], 12
	s_lshl_b64 s[0:1], s[2:3], 13
	s_add_u32 s0, s6, s0
	s_addc_u32 s1, s7, s1
	v_lshl_add_u64 v[64:65], s[0:1], 0, v[64:65]
	s_mov_b64 s[0:1], 0x1000
	v_lshl_add_u64 v[82:83], v[64:65], 0, s[0:1]
	s_lshl_b64 s[6:7], s[58:59], 13
	s_movk_i32 s3, 0xf800
	s_movk_i32 s8, 0xfc00
	v_mov_b32_e32 v96, 0x3727c5ac
	s_mov_b32 s9, 0xf800000
	v_mov_b32_e32 v97, 0x260
	v_add_co_u32_e32 v172, vcc, 0xfffff000, v82
	v_add_co_u32_e64 v174, s[0:1], s3, v82
	s_nop 0
	v_addc_co_u32_e32 v173, vcc, -1, v83, vcc
	v_add_co_u32_e32 v178, vcc, 0xfffff400, v82
	global_load_dwordx4 v[140:143], v[82:83], off
	v_addc_co_u32_e64 v175, s[0:1], -1, v83, s[0:1]
	global_load_dwordx4 v[144:147], v[82:83], off offset:1024
	global_load_dwordx4 v[148:151], v[82:83], off offset:2048
	global_load_dwordx4 v[152:155], v[82:83], off offset:3072
	global_load_dwordx4 v[156:159], v[172:173], off
	v_addc_co_u32_e32 v179, vcc, -1, v83, vcc
	v_add_co_u32_e64 v176, s[0:1], s8, v82
	global_load_dwordx4 v[160:163], v[174:175], off
	s_nop 0
	v_addc_co_u32_e64 v177, s[0:1], -1, v83, s[0:1]
	global_load_dwordx4 v[164:167], v[178:179], off
	global_load_dwordx4 v[168:171], v[176:177], off
	v_lshl_add_u64 v[82:83], v[82:83], 0, s[6:7]
	s_waitcnt vmcnt(0) lgkmcnt(0)
.LBB0_1036:
	v_mov_b64_e32 v[64:65], v[140:141]
	v_mov_b64_e32 v[66:67], v[142:143]
	v_mov_b64_e32 v[68:69], v[144:145]
	v_mov_b64_e32 v[70:71], v[146:147]
	v_mov_b64_e32 v[72:73], v[148:149]
	v_mov_b64_e32 v[74:75], v[150:151]
	v_mov_b64_e32 v[76:77], v[152:153]
	v_mov_b64_e32 v[78:79], v[154:155]
	v_mov_b64_e32 v[102:103], v[156:157]
	v_mov_b64_e32 v[104:105], v[158:159]
	v_mov_b64_e32 v[98:99], v[160:161]
	v_mov_b64_e32 v[100:101], v[162:163]
	v_mov_b64_e32 v[106:107], v[164:165]
	v_mov_b64_e32 v[108:109], v[166:167]
	v_mov_b64_e32 v[86:87], v[168:169]
	v_mov_b64_e32 v[88:89], v[170:171]
	s_add_i32 s2, s2, s58
	s_cmp_lt_i32 s2, 0x8000
	s_cbranch_scc0 .Lln_skip2
	v_add_co_u32_e32 v172, vcc, 0xfffff000, v82
	v_add_co_u32_e64 v174, s[0:1], s3, v82
	s_nop 0
	v_addc_co_u32_e32 v173, vcc, -1, v83, vcc
	v_add_co_u32_e32 v178, vcc, 0xfffff400, v82
	global_load_dwordx4 v[140:143], v[82:83], off
	v_addc_co_u32_e64 v175, s[0:1], -1, v83, s[0:1]
	global_load_dwordx4 v[144:147], v[82:83], off offset:1024
	global_load_dwordx4 v[148:151], v[82:83], off offset:2048
	global_load_dwordx4 v[152:155], v[82:83], off offset:3072
	global_load_dwordx4 v[156:159], v[172:173], off
	v_addc_co_u32_e32 v179, vcc, -1, v83, vcc
	v_add_co_u32_e64 v176, s[0:1], s8, v82
	global_load_dwordx4 v[160:163], v[174:175], off
	s_nop 0
	v_addc_co_u32_e64 v177, s[0:1], -1, v83, s[0:1]
	global_load_dwordx4 v[164:167], v[178:179], off
	global_load_dwordx4 v[168:171], v[176:177], off
	v_lshl_add_u64 v[82:83], v[82:83], 0, s[6:7]
; __device__ __forceinline__ void ln_phase(float* io, const float* g, const float* b, bf16_t* hb, float* stats, int gw, int NGW, int lane) {
;     ...
;         f32x4 v[8]; float s = 0.f;
; #pragma unroll
;         for (int j = 0; j < 8; ++j) { v[j] = xr[64 * j]; s += (v[j][0] + v[j][1]) + (v[j][2] + v[j][3]); }
;         const float mean = wave_sum(s, lane) * (1.f / D); float s2 = 0.f;
; #pragma unroll
;         for (int j = 0; j < 8; ++j) { v[j] = v[j] - mean; s2 += (v[j][0] * v[j][0] + v[j][1] * v[j][1]) + (v[j][2] * v[j][2] + v[j][3] * v[j][3]); }
;         const float rstd = 1.0f / sqrtf(wave_sum(s2, lane) * (1.f / D) + 1e-5f);
.Lln_skip2:
	v_mov_b32_e32 v111, v66
	v_mov_b32_e32 v113, v67
	v_mov_b32_e32 v114, v69
	v_mov_b32_e32 v115, v70
	v_mov_b32_e32 v116, v68
	v_mov_b32_e32 v117, v71
	v_add_f32_e32 v118, v72, v73
	v_add_f32_e32 v120, v74, v75
	v_mov_b32_e32 v119, v78
	v_mov_b32_e32 v121, v79
	v_pk_add_f32 v[114:115], v[114:115], v[116:117]
	v_pk_add_f32 v[116:117], v[118:119], v[120:121]
	v_mov_b32_e32 v118, v102
	v_mov_b32_e32 v120, v103
	v_mov_b32_e32 v126, v104
	v_mov_b32_e32 v128, v105
	v_mov_b32_e32 v119, v106
	v_mov_b32_e32 v121, v107
	v_mov_b32_e32 v127, v108
	v_mov_b32_e32 v129, v109
	v_mov_b32_e32 v122, v99
	v_mov_b32_e32 v123, v100
	v_mov_b32_e32 v124, v98
	v_mov_b32_e32 v125, v101
	v_pk_add_f32 v[118:119], v[118:119], v[120:121]
	v_pk_add_f32 v[120:121], v[126:127], v[128:129]
	v_add_f32_e32 v110, v86, v87
	v_add_f32_e32 v112, v88, v89
	v_pk_add_f32 v[122:123], v[122:123], v[124:125]
	v_pk_add_f32 v[118:119], v[118:119], v[120:121]
	v_pk_add_f32 v[110:111], v[110:111], v[112:113]
	v_pk_add_f32 v[112:113], v[114:115], v[114:115] op_sel:[0,1] op_sel_hi:[1,0]
	v_pk_add_f32 v[114:115], v[122:123], v[122:123] op_sel:[0,1] op_sel_hi:[1,0]
	v_add_f32_e32 v84, 0, v118
	v_mov_b32_e32 v85, v64
	v_mov_b32_e32 v115, v65
	v_add_f32_e32 v84, v84, v119
	v_pk_add_f32 v[84:85], v[84:85], v[114:115]
	v_mov_b32_e32 v113, v77
	v_pk_add_f32 v[84:85], v[84:85], v[110:111]
	s_nop 0
	v_pk_add_f32 v[84:85], v[84:85], v[84:85] op_sel:[0,1] op_sel_hi:[1,0]
	s_nop 0
	v_mov_b32_e32 v85, v76
	v_pk_add_f32 v[84:85], v[84:85], v[112:113]
	s_nop 0
	v_pk_add_f32 v[84:85], v[84:85], v[116:117]
	s_nop 0
	v_add_f32_e32 v84, v84, v85
	ds_bpermute_b32 v85, v90, v84
	s_waitcnt lgkmcnt(0)
	v_add_f32_e32 v84, v84, v85
	ds_bpermute_b32 v85, v91, v84
	s_waitcnt lgkmcnt(0)
	v_add_f32_e32 v84, v84, v85
	ds_bpermute_b32 v85, v92, v84
	s_waitcnt lgkmcnt(0)
	v_add_f32_e32 v84, v84, v85
	ds_bpermute_b32 v85, v93, v84
	s_waitcnt lgkmcnt(0)
	v_add_f32_e32 v84, v84, v85
	ds_bpermute_b32 v85, v94, v84
	s_waitcnt lgkmcnt(0)
	v_add_f32_e32 v84, v84, v85
	ds_bpermute_b32 v85, v95, v84
	s_waitcnt lgkmcnt(0)
	v_add_f32_e32 v110, v84, v85
	v_fmamk_f32 v85, v110, 0xba000000, v105
	v_fmamk_f32 v103, v110, 0xba000000, v103
	v_fmamk_f32 v105, v110, 0xba000000, v109
	v_fmamk_f32 v107, v110, 0xba000000, v107
	v_fmamk_f32 v84, v110, 0xba000000, v104
	v_fmac_f32_e32 v102, 0xba000000, v110
	v_fmamk_f32 v104, v110, 0xba000000, v108
	v_fmac_f32_e32 v106, 0xba000000, v110
	v_fmamk_f32 v99, v110, 0xba000000, v99
	v_fmamk_f32 v98, v110, 0xba000000, v98
	v_fmamk_f32 v101, v110, 0xba000000, v101
	v_fmac_f32_e32 v100, 0xba000000, v110
	v_fmamk_f32 v87, v110, 0xba000000, v87
	v_fmamk_f32 v86, v110, 0xba000000, v86
	v_fmamk_f32 v89, v110, 0xba000000, v89
	v_fmac_f32_e32 v88, 0xba000000, v110
	v_fmamk_f32 v67, v110, 0xba000000, v67
	v_fmamk_f32 v66, v110, 0xba000000, v66
	v_fmamk_f32 v65, v110, 0xba000000, v65
	v_fmac_f32_e32 v64, 0xba000000, v110
	v_fmamk_f32 v69, v110, 0xba000000, v69
	v_fmamk_f32 v68, v110, 0xba000000, v68
	v_fmamk_f32 v71, v110, 0xba000000, v71
	v_fmac_f32_e32 v70, 0xba000000, v110
	v_fmamk_f32 v73, v110, 0xba000000, v73
	v_fmamk_f32 v72, v110, 0xba000000, v72
	v_fmamk_f32 v75, v110, 0xba000000, v75
	v_fmac_f32_e32 v74, 0xba000000, v110
	v_fmamk_f32 v79, v110, 0xba000000, v79
	v_fmamk_f32 v78, v110, 0xba000000, v78
	v_fmamk_f32 v77, v110, 0xba000000, v77
	v_fmac_f32_e32 v76, 0xba000000, v110
	v_mov_b32_e32 v110, v103
	v_mov_b32_e32 v111, v107
	v_mov_b32_e32 v114, v85
	v_mov_b32_e32 v115, v105
	v_mov_b32_e32 v108, v102
	v_mov_b32_e32 v109, v106
	v_mov_b32_e32 v112, v84
	v_mov_b32_e32 v113, v104
	v_pk_mul_f32 v[116:117], v[100:101], v[100:101]
	v_pk_mul_f32 v[118:119], v[98:99], v[98:99]
	v_pk_mul_f32 v[110:111], v[110:111], v[110:111]
	v_pk_mul_f32 v[114:115], v[114:115], v[114:115]
	v_pk_mov_b32 v[132:133], v[118:119], v[116:117] op_sel:[1,0]
	v_mov_b32_e32 v119, v117
	v_pk_fma_f32 v[108:109], v[108:109], v[108:109], v[110:111]
	v_pk_fma_f32 v[110:111], v[112:113], v[112:113], v[114:115]
	v_mul_f32_e32 v120, v86, v86
	v_mul_f32_e32 v122, v88, v88
	v_pk_add_f32 v[112:113], v[132:133], v[118:119]
	v_pk_add_f32 v[108:109], v[108:109], v[110:111]
	v_pk_fma_f32 v[116:117], v[86:87], v[86:87], v[120:121] op_sel_hi:[1,1,0]
	v_pk_fma_f32 v[120:121], v[88:89], v[88:89], v[122:123] op_sel_hi:[1,1,0]
	v_pk_add_f32 v[110:111], v[112:113], v[112:113] op_sel_hi:[0,1]
	v_pk_add_f32 v[108:109], v[108:109], v[108:109] op_sel_hi:[0,1]
	v_pk_mul_f32 v[124:125], v[70:71], v[70:71]
	v_pk_mul_f32 v[126:127], v[68:69], v[68:69]
	v_mul_f32_e32 v116, v64, v64
	v_mul_f32_e32 v120, v65, v65
	v_mul_f32_e32 v110, v66, v66
	v_mul_f32_e32 v108, v67, v67
	v_pk_mov_b32 v[122:123], v[126:127], v[124:125] op_sel:[1,0]
	v_mov_b32_e32 v127, v125
	v_pk_add_f32 v[112:113], v[116:117], v[120:121]
	v_pk_add_f32 v[108:109], v[110:111], v[108:109]
	v_mul_f32_e32 v128, v72, v72
	v_mul_f32_e32 v130, v74, v74
	v_pk_add_f32 v[114:115], v[122:123], v[126:127]
	v_pk_add_f32 v[108:109], v[112:113], v[108:109]
	v_pk_fma_f32 v[124:125], v[72:73], v[72:73], v[128:129] op_sel_hi:[1,1,0]
	v_pk_fma_f32 v[128:129], v[74:75], v[74:75], v[130:131] op_sel_hi:[1,1,0]
	v_pk_add_f32 v[114:115], v[114:115], v[114:115] op_sel_hi:[0,1]
	v_pk_add_f32 v[108:109], v[108:109], v[108:109] op_sel_hi:[0,1]
	v_mul_f32_e32 v124, v76, v76
	v_mul_f32_e32 v128, v77, v77
	v_mul_f32_e32 v114, v78, v78
	v_mul_f32_e32 v108, v79, v79
	v_pk_add_f32 v[116:117], v[124:125], v[128:129]
	v_pk_add_f32 v[108:109], v[114:115], v[108:109]
	s_nop 0
	v_pk_add_f32 v[108:109], v[116:117], v[108:109]
	s_nop 0
	v_add_f32_e32 v108, v108, v109
	ds_bpermute_b32 v109, v90, v108
	s_waitcnt lgkmcnt(0)
; __device__ __forceinline__ unsigned cvt_pk_bf16(float lo, float hi) { unsigned r; asm volatile("s_nop 1\n\tv_cvt_pk_bf16_f32 %0, %1, %2" : "=v"(r) : "v"(lo), "v"(hi)); return r; }
; __device__ __forceinline__ void ln_phase(float* io, const float* g, const float* b, bf16_t* hb, float* stats, int gw, int NGW, int lane) {
;     ...
;         const float rstd = 1.0f / sqrtf(wave_sum(s2, lane) * (1.f / D) + 1e-5f);
; #pragma unroll
;         for (int j = 0; j < 8; ++j) v[j] = v[j] * rstd * gv[j] + bv[j];
;         if (stats) {
;             u32x2* o8 = (u32x2*)(hb + (size_t)row * D) + lane;
; #pragma unroll
;             for (int j = 0; j < 8; ++j) { u32x2 w; w.x = cvt_pk_bf16(v[j][0], v[j][1]); w.y = cvt_pk_bf16(v[j][2], v[j][3]); o8[64 * j] = w; }
	v_add_f32_e32 v108, v108, v109
	ds_bpermute_b32 v109, v91, v108
	s_waitcnt lgkmcnt(0)
	v_add_f32_e32 v108, v108, v109
	ds_bpermute_b32 v109, v92, v108
	s_waitcnt lgkmcnt(0)
	v_add_f32_e32 v108, v108, v109
	ds_bpermute_b32 v109, v93, v108
	s_waitcnt lgkmcnt(0)
	v_add_f32_e32 v108, v108, v109
	ds_bpermute_b32 v109, v94, v108
	s_waitcnt lgkmcnt(0)
	v_add_f32_e32 v108, v108, v109
	ds_bpermute_b32 v109, v95, v108
	s_waitcnt lgkmcnt(0)
	v_add_f32_e32 v108, v108, v109
	v_fmamk_f32 v108, v108, 0x3a000000, v96
	v_mul_f32_e32 v109, 0x4f800000, v108
	v_cmp_gt_f32_e32 vcc, s9, v108
	s_nop 1
	v_cndmask_b32_e32 v108, v108, v109, vcc
	v_sqrt_f32_e32 v109, v108
	s_nop 0
	v_add_u32_e32 v110, -1, v109
	v_add_u32_e32 v111, 1, v109
	v_fma_f32 v112, -v110, v109, v108
	v_fma_f32 v113, -v111, v109, v108
	v_cmp_ge_f32_e64 s[0:1], 0, v112
	s_nop 1
	v_cndmask_b32_e64 v109, v109, v110, s[0:1]
	v_cmp_lt_f32_e64 s[0:1], 0, v113
	s_nop 1
	v_cndmask_b32_e64 v109, v109, v111, s[0:1]
	v_mul_f32_e32 v110, 0x37800000, v109
	v_cndmask_b32_e32 v109, v109, v110, vcc
	v_cmp_class_f32_e32 vcc, v108, v97
	s_nop 1
	v_cndmask_b32_e32 v108, v109, v108, vcc
	v_div_scale_f32 v109, s[0:1], v108, v108, 1.0
	v_rcp_f32_e32 v111, v109
	v_div_scale_f32 v110, vcc, 1.0, v108, 1.0
	v_fma_f32 v112, -v109, v111, 1.0
	v_fmac_f32_e32 v111, v112, v111
	v_mul_f32_e32 v112, v110, v111
	v_fma_f32 v113, -v109, v112, v110
	v_fmac_f32_e32 v112, v113, v111
	v_fma_f32 v109, -v109, v112, v110
	v_div_fmas_f32 v109, v109, v111, v112
	v_div_fixup_f32 v108, v109, v108, 1.0
	v_pk_mul_f32 v[84:85], v[84:85], v[108:109] op_sel_hi:[1,0]
	v_pk_mul_f32 v[102:103], v[102:103], v[108:109] op_sel_hi:[1,0]
	v_pk_mul_f32 v[104:105], v[104:105], v[108:109] op_sel_hi:[1,0]
	v_pk_mul_f32 v[106:107], v[106:107], v[108:109] op_sel_hi:[1,0]
	v_pk_fma_f32 v[102:103], v[0:1], v[102:103], v[4:5]
	v_pk_fma_f32 v[84:85], v[2:3], v[84:85], v[6:7]
	v_pk_mul_f32 v[100:101], v[100:101], v[108:109] op_sel_hi:[1,0]
	v_pk_mul_f32 v[98:99], v[98:99], v[108:109] op_sel_hi:[1,0]
	v_pk_mul_f32 v[64:65], v[64:65], v[108:109] op_sel_hi:[1,0]
	v_pk_fma_f32 v[106:107], v[8:9], v[106:107], v[16:17]
	v_pk_fma_f32 v[104:105], v[10:11], v[104:105], v[18:19]
	s_nop 1
	v_cvt_pk_bf16_f32 v102, v102, v103
	s_nop 1
	v_cvt_pk_bf16_f32 v103, v84, v85
	global_store_dwordx2 v[80:81], v[102:103], off
	s_nop 1
	v_cvt_pk_bf16_f32 v84, v106, v107
	s_nop 1
	v_cvt_pk_bf16_f32 v85, v104, v105
	v_pk_mul_f32 v[88:89], v[88:89], v[108:109] op_sel_hi:[1,0]
	v_pk_mul_f32 v[86:87], v[86:87], v[108:109] op_sel_hi:[1,0]
	v_pk_mul_f32 v[66:67], v[66:67], v[108:109] op_sel_hi:[1,0]
	v_pk_fma_f32 v[98:99], v[12:13], v[98:99], v[20:21]
	v_pk_fma_f32 v[100:101], v[14:15], v[100:101], v[22:23]
	v_pk_fma_f32 v[64:65], v[32:33], v[64:65], v[40:41]
	global_store_dwordx2 v[80:81], v[84:85], off offset:512
	s_nop 1
	v_cvt_pk_bf16_f32 v84, v98, v99
	s_nop 1
	v_cvt_pk_bf16_f32 v85, v100, v101
	v_pk_mul_f32 v[70:71], v[70:71], v[108:109] op_sel_hi:[1,0]
	v_pk_mul_f32 v[68:69], v[68:69], v[108:109] op_sel_hi:[1,0]
	v_pk_fma_f32 v[86:87], v[24:25], v[86:87], v[28:29]
	v_pk_fma_f32 v[88:89], v[26:27], v[88:89], v[30:31]
	v_pk_fma_f32 v[66:67], v[34:35], v[66:67], v[42:43]
	global_store_dwordx2 v[80:81], v[84:85], off offset:1024
	s_nop 1
	v_cvt_pk_bf16_f32 v84, v86, v87
	s_nop 1
	v_cvt_pk_bf16_f32 v85, v88, v89
	global_store_dwordx2 v[80:81], v[84:85], off offset:1536
	s_nop 1
	v_cvt_pk_bf16_f32 v64, v64, v65
	s_nop 1
	v_cvt_pk_bf16_f32 v65, v66, v67
	v_pk_mul_f32 v[74:75], v[74:75], v[108:109] op_sel_hi:[1,0]
	v_pk_mul_f32 v[72:73], v[72:73], v[108:109] op_sel_hi:[1,0]
	v_pk_fma_f32 v[68:69], v[36:37], v[68:69], v[44:45]
	v_pk_fma_f32 v[70:71], v[38:39], v[70:71], v[46:47]
	global_store_dwordx2 v[80:81], v[64:65], off offset:2048
	s_nop 1
	v_cvt_pk_bf16_f32 v64, v68, v69
	s_nop 1
	v_cvt_pk_bf16_f32 v65, v70, v71
	v_pk_mul_f32 v[78:79], v[78:79], v[108:109] op_sel_hi:[1,0]
	v_pk_mul_f32 v[76:77], v[76:77], v[108:109] op_sel_hi:[1,0]
	v_pk_fma_f32 v[72:73], v[48:49], v[72:73], v[56:57]
	v_pk_fma_f32 v[74:75], v[50:51], v[74:75], v[58:59]
	global_store_dwordx2 v[80:81], v[64:65], off offset:2560
	s_nop 1
	v_cvt_pk_bf16_f32 v64, v72, v73
	s_nop 1
	v_cvt_pk_bf16_f32 v65, v74, v75
	v_pk_fma_f32 v[76:77], v[52:53], v[76:77], v[60:61]
	v_pk_fma_f32 v[78:79], v[54:55], v[78:79], v[62:63]
	global_store_dwordx2 v[80:81], v[64:65], off offset:3072
	s_nop 1
	v_cvt_pk_bf16_f32 v64, v76, v77
	s_nop 1
	v_cvt_pk_bf16_f32 v65, v78, v79
	global_store_dwordx2 v[80:81], v[64:65], off offset:3584
	v_lshl_add_u64 v[80:81], v[80:81], 0, s[4:5]
	s_waitcnt vmcnt(8)
	s_cmp_lt_i32 s2, 0x8000
	s_cbranch_scc1 .LBB0_1036
	v_readlane_b32 s59, v254, 0

; __device__ __forceinline__ void ln_phase(float* io, const float* g, const float* b, bf16_t* hb, float* stats, int gw, int NGW, int lane) {
;     f32x4 gv[8], bv[8];
; #pragma unroll
;     for (int j = 0; j < 8; ++j) { gv[j] = *((const f32x4*)g + lane + 64 * j); bv[j] = *((const f32x4*)b + lane + 64 * j); }
;     for (int row = gw; row < M; row += NGW) {
;         f32x4* xr = (f32x4*)(io + (size_t)row * D) + lane;
;         f32x4 v[8]; float s = 0.f;
; #pragma unroll
;         for (int j = 0; j < 8; ++j) { v[j] = xr[64 * j]; s += (v[j][0] + v[j][1]) + (v[j][2] + v[j][3]); }
;         const float mean = wave_sum(s, lane) * (1.f / D); float s2 = 0.f;
.LBB0_1150:
	s_or_b64 exec, exec, s[30:31]
	s_add_i32 s0, 0, 0x23088
	v_mov_b32_e32 v2, s0
	s_add_i32 s0, 0, 0x2308c
	s_waitcnt lgkmcnt(0)
	s_barrier
	v_mbcnt_lo_u32_b32 v0, -1, 0
	v_mbcnt_hi_u32_b32 v0, -1, v0
	ds_read_b32 v2, v2
	v_or_b32_e32 v1, s59, v0
	v_mov_b32_e32 v3, s0
	ds_read_b32 v3, v3
	v_readfirstlane_b32 s0, v1
	s_ashr_i32 s0, s0, 6
	v_readlane_b32 s1, v254, 1
	s_add_i32 s2, s0, s1
	s_add_i32 s0, 0, 0x23018
	v_mov_b32_e32 v1, s0
	s_add_i32 s0, 0, 0x2301c
	s_waitcnt lgkmcnt(0)
	v_readfirstlane_b32 s6, v2
	v_mov_b32_e32 v2, s0
	s_add_i32 s0, 0, 0x23020
	v_readfirstlane_b32 s7, v3
	v_mov_b32_e32 v3, s0
	s_add_i32 s0, 0, 0x23024
	v_mov_b32_e32 v4, s0
	ds_read_b32 v1, v1
	ds_read_b32 v2, v2
	ds_read_b32 v3, v3
	ds_read_b32 v4, v4
	s_cmpk_gt_i32 s2, 0x7fff
	s_waitcnt lgkmcnt(0)
	v_readfirstlane_b32 s4, v1
	v_readfirstlane_b32 s5, v2
	v_readfirstlane_b32 s0, v3
	v_readfirstlane_b32 s1, v4
	s_cbranch_scc1 .LBB0_1153
	v_and_b32_e32 v70, 63, v0
	v_lshlrev_b32_e32 v64, 4, v70
	v_mov_b32_e32 v65, 0
	v_lshl_add_u64 v[32:33], s[4:5], 0, v[64:65]
	v_add_co_u32_e32 v0, vcc, 0x6000, v32
	v_lshl_add_u64 v[36:37], s[0:1], 0, v[64:65]
	s_nop 0
	v_addc_co_u32_e32 v1, vcc, 0, v33, vcc
	v_add_co_u32_e32 v40, vcc, 0x6000, v36
	s_mov_b64 s[4:5], 0x6000
	s_nop 0
	v_addc_co_u32_e32 v41, vcc, 0, v37, vcc
	v_add_co_u32_e32 v66, vcc, 0x7000, v32
	v_lshl_add_u64 v[34:35], v[32:33], 0, s[4:5]
	s_nop 0
	v_addc_co_u32_e32 v67, vcc, 0, v33, vcc
	v_lshl_add_u64 v[38:39], v[36:37], 0, s[4:5]
	v_add_co_u32_e32 v68, vcc, 0x7000, v36
	flat_load_dwordx4 v[0:3], v[0:1]
	s_nop 0
	flat_load_dwordx4 v[4:7], v[40:41]
	flat_load_dwordx4 v[8:11], v[34:35] offset:1024
	flat_load_dwordx4 v[12:15], v[34:35] offset:2048
	flat_load_dwordx4 v[16:19], v[38:39] offset:1024
	flat_load_dwordx4 v[20:23], v[38:39] offset:2048
	flat_load_dwordx4 v[24:27], v[34:35] offset:3072
	flat_load_dwordx4 v[28:31], v[38:39] offset:3072
	v_addc_co_u32_e32 v69, vcc, 0, v37, vcc
	flat_load_dwordx4 v[32:35], v[66:67]
	flat_load_dwordx4 v[36:39], v[66:67] offset:1024
	flat_load_dwordx4 v[40:43], v[68:69]
	flat_load_dwordx4 v[44:47], v[68:69] offset:1024
	flat_load_dwordx4 v[48:51], v[66:67] offset:2048
	flat_load_dwordx4 v[52:55], v[66:67] offset:3072
	flat_load_dwordx4 v[56:59], v[68:69] offset:2048
	flat_load_dwordx4 v[60:63], v[68:69] offset:3072
	s_ashr_i32 s3, s2, 31
	s_lshl_b64 s[0:1], s[2:3], 13
	s_add_u32 s0, s6, s0
	v_lshlrev_b32_e32 v66, 2, v70
	s_addc_u32 s1, s7, s1
	s_ashr_i32 s59, s58, 31
	v_xor_b32_e32 v100, 4, v66
	v_xor_b32_e32 v101, 8, v66
	v_xor_b32_e32 v102, 16, v66
	v_xor_b32_e32 v103, 32, v66
	v_xor_b32_e32 v104, 64, v66
	v_xor_b32_e32 v105, 0x80, v66
	v_lshl_add_u64 v[96:97], s[0:1], 0, v[64:65]
	s_lshl_b64 s[4:5], s[58:59], 13
	s_movk_i32 s3, 0x1000
	v_mov_b32_e32 v106, 0x3727c5ac
	s_mov_b32 s6, 0xf800000
	v_mov_b32_e32 v107, 0x260
	v_add_co_u32_e32 v98, vcc, s3, v96
	s_nop 0
	v_addc_co_u32_e32 v99, vcc, 0, v97, vcc
	global_load_dwordx4 v[140:143], v[96:97], off
	global_load_dwordx4 v[144:147], v[96:97], off offset:1024
	global_load_dwordx4 v[148:151], v[96:97], off offset:2048
	global_load_dwordx4 v[152:155], v[96:97], off offset:3072
	global_load_dwordx4 v[156:159], v[98:99], off
	global_load_dwordx4 v[160:163], v[98:99], off offset:1024
	global_load_dwordx4 v[164:167], v[98:99], off offset:2048
	global_load_dwordx4 v[168:171], v[98:99], off offset:3072
	s_waitcnt vmcnt(0) lgkmcnt(0)
.LBB0_1152:
	v_mov_b64_e32 v[84:85], v[140:141]
	v_mov_b64_e32 v[86:87], v[142:143]
	v_mov_b64_e32 v[64:65], v[144:145]
	v_mov_b64_e32 v[66:67], v[146:147]
	v_mov_b64_e32 v[92:93], v[148:149]
	v_mov_b64_e32 v[94:95], v[150:151]
	v_mov_b64_e32 v[76:77], v[152:153]
	v_mov_b64_e32 v[78:79], v[154:155]
	v_mov_b64_e32 v[72:73], v[156:157]
	v_mov_b64_e32 v[74:75], v[158:159]
	v_mov_b64_e32 v[80:81], v[160:161]
	v_mov_b64_e32 v[82:83], v[162:163]
	v_mov_b64_e32 v[88:89], v[164:165]
	v_mov_b64_e32 v[90:91], v[166:167]
	v_mov_b64_e32 v[68:69], v[168:169]
	v_mov_b64_e32 v[70:71], v[170:171]
	v_add_co_u32_e32 v98, vcc, s3, v96
	s_nop 0
	v_addc_co_u32_e32 v99, vcc, 0, v97, vcc
	s_add_i32 s2, s2, s58
	s_cmp_lt_i32 s2, 0x8000
	s_cbranch_scc0 .Lln_skip3
	v_lshl_add_u64 v[172:173], v[96:97], 0, s[4:5]
	v_add_co_u32_e32 v174, vcc, s3, v172
	s_nop 0
	v_addc_co_u32_e32 v175, vcc, 0, v173, vcc
	global_load_dwordx4 v[140:143], v[172:173], off
	global_load_dwordx4 v[144:147], v[172:173], off offset:1024
	global_load_dwordx4 v[148:151], v[172:173], off offset:2048
	global_load_dwordx4 v[152:155], v[172:173], off offset:3072
	global_load_dwordx4 v[156:159], v[174:175], off
	global_load_dwordx4 v[160:163], v[174:175], off offset:1024
	global_load_dwordx4 v[164:167], v[174:175], off offset:2048
	global_load_dwordx4 v[168:171], v[174:175], off offset:3072
; __device__ __forceinline__ void ln_phase(float* io, const float* g, const float* b, bf16_t* hb, float* stats, int gw, int NGW, int lane) {
;     ...
;         f32x4 v[8]; float s = 0.f;
; #pragma unroll
;         for (int j = 0; j < 8; ++j) { v[j] = xr[64 * j]; s += (v[j][0] + v[j][1]) + (v[j][2] + v[j][3]); }
;         const float mean = wave_sum(s, lane) * (1.f / D); float s2 = 0.f;
; #pragma unroll
;         for (int j = 0; j < 8; ++j) { v[j] = v[j] - mean; s2 += (v[j][0] * v[j][0] + v[j][1] * v[j][1]) + (v[j][2] * v[j][2] + v[j][3] * v[j][3]); }
;         const float rstd = 1.0f / sqrtf(wave_sum(s2, lane) * (1.f / D) + 1e-5f);
.Lln_skip3:
	v_mov_b32_e32 v108, v84
	v_mov_b32_e32 v109, v64
	v_mov_b32_e32 v110, v85
	v_mov_b32_e32 v111, v65
	v_mov_b32_e32 v112, v86
	v_mov_b32_e32 v113, v66
	v_mov_b32_e32 v114, v87
	v_mov_b32_e32 v115, v67
	v_mov_b32_e32 v116, v93
	v_mov_b32_e32 v117, v94
	v_mov_b32_e32 v118, v92
	v_mov_b32_e32 v119, v95
	v_pk_add_f32 v[108:109], v[108:109], v[110:111]
	v_pk_add_f32 v[110:111], v[112:113], v[114:115]
	v_pk_add_f32 v[112:113], v[116:117], v[118:119]
	v_pk_add_f32 v[108:109], v[108:109], v[110:111]
	v_pk_add_f32 v[110:111], v[112:113], v[112:113] op_sel:[0,1] op_sel_hi:[1,0]
	v_add_f32_e32 v108, 0, v108
	v_add_f32_e32 v120, v76, v77
	v_add_f32_e32 v122, v78, v79
	v_mov_b32_e32 v115, v72
	v_mov_b32_e32 v121, v74
	v_mov_b32_e32 v123, v75
	v_mov_b32_e32 v111, v73
	v_add_f32_e32 v114, v108, v109
	v_mov_b32_e32 v116, v81
	v_mov_b32_e32 v117, v82
	v_mov_b32_e32 v118, v80
	v_mov_b32_e32 v119, v83
	v_pk_add_f32 v[112:113], v[120:121], v[122:123]
	v_pk_add_f32 v[108:109], v[114:115], v[110:111]
	v_pk_add_f32 v[116:117], v[116:117], v[118:119]
	v_pk_add_f32 v[108:109], v[108:109], v[112:113]
	v_pk_add_f32 v[116:117], v[116:117], v[116:117] op_sel:[0,1] op_sel_hi:[1,0]
	v_pk_add_f32 v[108:109], v[108:109], v[108:109] op_sel:[0,1] op_sel_hi:[1,0]
	v_add_f32_e32 v124, v88, v89
	v_add_f32_e32 v126, v90, v91
	v_mov_b32_e32 v125, v70
	v_mov_b32_e32 v127, v71
	v_mov_b32_e32 v117, v69
	v_mov_b32_e32 v109, v68
	v_pk_add_f32 v[118:119], v[124:125], v[126:127]
	v_pk_add_f32 v[108:109], v[108:109], v[116:117]
	s_nop 0
	v_pk_add_f32 v[108:109], v[108:109], v[118:119]
	s_nop 0
	v_add_f32_e32 v108, v108, v109
	ds_bpermute_b32 v109, v100, v108
	s_waitcnt lgkmcnt(0)
	v_add_f32_e32 v108, v108, v109
	ds_bpermute_b32 v109, v101, v108
	s_waitcnt lgkmcnt(0)
	v_add_f32_e32 v108, v108, v109
	ds_bpermute_b32 v109, v102, v108
	s_waitcnt lgkmcnt(0)
	v_add_f32_e32 v108, v108, v109
	ds_bpermute_b32 v109, v103, v108
	s_waitcnt lgkmcnt(0)
	v_add_f32_e32 v108, v108, v109
	ds_bpermute_b32 v109, v104, v108
	s_waitcnt lgkmcnt(0)
	v_add_f32_e32 v108, v108, v109
	ds_bpermute_b32 v109, v105, v108
	s_waitcnt lgkmcnt(0)
	v_add_f32_e32 v129, v108, v109
	v_fmamk_f32 v87, v129, 0xba000000, v87
	v_fmamk_f32 v85, v129, 0xba000000, v85
	v_fmamk_f32 v67, v129, 0xba000000, v67
	v_fmamk_f32 v65, v129, 0xba000000, v65
	v_fmamk_f32 v86, v129, 0xba000000, v86
	v_fmac_f32_e32 v84, 0xba000000, v129
	v_fmamk_f32 v66, v129, 0xba000000, v66
	v_fmac_f32_e32 v64, 0xba000000, v129
	v_fmamk_f32 v93, v129, 0xba000000, v93
	v_fmamk_f32 v92, v129, 0xba000000, v92
	v_fmamk_f32 v95, v129, 0xba000000, v95
	v_fmac_f32_e32 v94, 0xba000000, v129
	v_fmamk_f32 v111, v129, 0xba000000, v81
	v_fmamk_f32 v110, v129, 0xba000000, v80
	v_mov_b32_e32 v80, v85
	v_mov_b32_e32 v81, v65
	v_mov_b32_e32 v114, v87
	v_mov_b32_e32 v115, v67
	v_fmamk_f32 v109, v129, 0xba000000, v75
	v_fmamk_f32 v108, v129, 0xba000000, v74
	v_mov_b32_e32 v74, v84
	v_mov_b32_e32 v75, v64
	v_mov_b32_e32 v112, v86
	v_mov_b32_e32 v113, v66
	v_pk_mul_f32 v[116:117], v[94:95], v[94:95]
	v_pk_mul_f32 v[118:119], v[92:93], v[92:93]
	v_pk_mul_f32 v[80:81], v[80:81], v[80:81]
	v_pk_mul_f32 v[114:115], v[114:115], v[114:115]
	v_fmamk_f32 v76, v129, 0xba000000, v76
	v_fmac_f32_e32 v78, 0xba000000, v129
	v_pk_mov_b32 v[132:133], v[118:119], v[116:117] op_sel:[1,0]
	v_mov_b32_e32 v119, v117
	v_pk_fma_f32 v[74:75], v[74:75], v[74:75], v[80:81]
	v_pk_fma_f32 v[80:81], v[112:113], v[112:113], v[114:115]
	v_fmamk_f32 v77, v129, 0xba000000, v77
	v_fmamk_f32 v79, v129, 0xba000000, v79
	v_mul_f32_e32 v120, v76, v76
	v_mul_f32_e32 v122, v78, v78
	v_pk_add_f32 v[112:113], v[132:133], v[118:119]
	v_pk_add_f32 v[74:75], v[74:75], v[80:81]
	v_fmamk_f32 v73, v129, 0xba000000, v73
	v_fmac_f32_e32 v72, 0xba000000, v129
	v_fmamk_f32 v83, v129, 0xba000000, v83
	v_fmac_f32_e32 v82, 0xba000000, v129
	v_pk_fma_f32 v[116:117], v[76:77], v[76:77], v[120:121] op_sel_hi:[1,1,0]
	v_pk_fma_f32 v[120:121], v[78:79], v[78:79], v[122:123] op_sel_hi:[1,1,0]
	v_pk_add_f32 v[80:81], v[112:113], v[112:113] op_sel_hi:[0,1]
	v_pk_add_f32 v[74:75], v[74:75], v[74:75] op_sel_hi:[0,1]
	v_pk_mul_f32 v[124:125], v[82:83], v[82:83]
	v_pk_mul_f32 v[126:127], v[110:111], v[110:111]
	v_mul_f32_e32 v116, v72, v72
	v_mul_f32_e32 v120, v73, v73
	v_mul_f32_e32 v80, v108, v108
	v_mul_f32_e32 v74, v109, v109
	v_fmamk_f32 v88, v129, 0xba000000, v88
	v_fmac_f32_e32 v90, 0xba000000, v129
	v_pk_mov_b32 v[122:123], v[126:127], v[124:125] op_sel:[1,0]
	v_mov_b32_e32 v127, v125
	v_pk_add_f32 v[112:113], v[116:117], v[120:121]
	v_pk_add_f32 v[74:75], v[80:81], v[74:75]
	v_fmamk_f32 v89, v129, 0xba000000, v89
	v_fmamk_f32 v91, v129, 0xba000000, v91
	v_mul_f32_e32 v128, v88, v88
	v_mul_f32_e32 v130, v90, v90
	v_pk_add_f32 v[114:115], v[122:123], v[126:127]
	v_pk_add_f32 v[74:75], v[112:113], v[74:75]
	v_pk_fma_f32 v[124:125], v[88:89], v[88:89], v[128:129] op_sel_hi:[1,1,0]
	v_pk_add_f32 v[114:115], v[114:115], v[114:115] op_sel_hi:[0,1]
	v_pk_add_f32 v[74:75], v[74:75], v[74:75] op_sel_hi:[0,1]
	v_pk_fma_f32 v[80:81], v[90:91], v[90:91], v[130:131] op_sel_hi:[1,1,0]
	v_fmamk_f32 v113, v129, 0xba000000, v71
	v_fmamk_f32 v112, v129, 0xba000000, v70
	v_fmamk_f32 v69, v129, 0xba000000, v69
	v_fmac_f32_e32 v68, 0xba000000, v129
	v_mul_f32_e32 v124, v68, v68
	v_mul_f32_e32 v80, v69, v69
	v_mul_f32_e32 v114, v112, v112
	v_mul_f32_e32 v74, v113, v113
	v_pk_add_f32 v[70:71], v[124:125], v[80:81]
	v_pk_add_f32 v[74:75], v[114:115], v[74:75]
	s_nop 0
	v_pk_add_f32 v[70:71], v[70:71], v[74:75]
	s_nop 0
	v_add_f32_e32 v70, v70, v71
	ds_bpermute_b32 v71, v100, v70
	s_waitcnt lgkmcnt(0)
; __device__ __forceinline__ unsigned cvt_pk_bf16(float lo, float hi) { unsigned r; asm volatile("s_nop 1\n\tv_cvt_pk_bf16_f32 %0, %1, %2" : "=v"(r) : "v"(lo), "v"(hi)); return r; }
; __device__ __forceinline__ void ln_phase(float* io, const float* g, const float* b, bf16_t* hb, float* stats, int gw, int NGW, int lane) {
;     ...
;         const float rstd = 1.0f / sqrtf(wave_sum(s2, lane) * (1.f / D) + 1e-5f);
; #pragma unroll
;         for (int j = 0; j < 8; ++j) v[j] = v[j] * rstd * gv[j] + bv[j];
;         if (stats) {
;             u32x2* o8 = (u32x2*)(hb + (size_t)row * D) + lane;
; #pragma unroll
;             for (int j = 0; j < 8; ++j) { u32x2 w; w.x = cvt_pk_bf16(v[j][0], v[j][1]); w.y = cvt_pk_bf16(v[j][2], v[j][3]); o8[64 * j] = w; }
;         } else {
; #pragma unroll
;             for (int j = 0; j < 8; ++j) xr[64 * j] = v[j];
	v_add_f32_e32 v70, v70, v71
	ds_bpermute_b32 v71, v101, v70
	s_waitcnt lgkmcnt(0)
	v_add_f32_e32 v70, v70, v71
	ds_bpermute_b32 v71, v102, v70
	s_waitcnt lgkmcnt(0)
	v_add_f32_e32 v70, v70, v71
	ds_bpermute_b32 v71, v103, v70
	s_waitcnt lgkmcnt(0)
	v_add_f32_e32 v70, v70, v71
	ds_bpermute_b32 v71, v104, v70
	s_waitcnt lgkmcnt(0)
	v_add_f32_e32 v70, v70, v71
	ds_bpermute_b32 v71, v105, v70
	s_waitcnt lgkmcnt(0)
	v_add_f32_e32 v70, v70, v71
	v_fmamk_f32 v70, v70, 0x3a000000, v106
	v_mul_f32_e32 v71, 0x4f800000, v70
	v_cmp_gt_f32_e32 vcc, s6, v70
	s_nop 1
	v_cndmask_b32_e32 v70, v70, v71, vcc
	v_sqrt_f32_e32 v71, v70
	s_nop 0
	v_add_u32_e32 v74, -1, v71
	v_add_u32_e32 v75, 1, v71
	v_fma_f32 v80, -v74, v71, v70
	v_fma_f32 v81, -v75, v71, v70
	v_cmp_ge_f32_e64 s[0:1], 0, v80
	s_nop 1
	v_cndmask_b32_e64 v71, v71, v74, s[0:1]
	v_cmp_lt_f32_e64 s[0:1], 0, v81
	s_nop 1
	v_cndmask_b32_e64 v71, v71, v75, s[0:1]
	v_mul_f32_e32 v74, 0x37800000, v71
	v_cndmask_b32_e32 v71, v71, v74, vcc
	v_cmp_class_f32_e32 vcc, v70, v107
	s_nop 1
	v_cndmask_b32_e32 v70, v71, v70, vcc
	v_div_scale_f32 v71, s[0:1], v70, v70, 1.0
	v_rcp_f32_e32 v74, v71
	v_div_scale_f32 v75, vcc, 1.0, v70, 1.0
	v_fma_f32 v80, -v71, v74, 1.0
	v_fmac_f32_e32 v74, v80, v74
	v_mul_f32_e32 v80, v75, v74
	v_fma_f32 v81, -v71, v80, v75
	v_fmac_f32_e32 v80, v81, v74
	v_fma_f32 v71, -v71, v80, v75
	v_div_fmas_f32 v71, v71, v74, v80
	v_div_fixup_f32 v114, v71, v70, 1.0
	v_pk_mul_f32 v[70:71], v[84:85], v[114:115] op_sel_hi:[1,0]
	v_pk_mul_f32 v[74:75], v[86:87], v[114:115] op_sel_hi:[1,0]
	v_pk_mul_f32 v[86:87], v[94:95], v[114:115] op_sel_hi:[1,0]
	v_pk_mul_f32 v[94:95], v[76:77], v[114:115] op_sel_hi:[1,0]
	v_pk_mul_f32 v[82:83], v[82:83], v[114:115] op_sel_hi:[1,0]
	v_pk_mul_f32 v[80:81], v[64:65], v[114:115] op_sel_hi:[1,0]
	v_pk_mul_f32 v[84:85], v[66:67], v[114:115] op_sel_hi:[1,0]
	v_pk_mul_f32 v[92:93], v[92:93], v[114:115] op_sel_hi:[1,0]
	v_pk_fma_f32 v[64:65], v[0:1], v[70:71], v[4:5]
	v_pk_mul_f32 v[70:71], v[78:79], v[114:115] op_sel_hi:[1,0]
	v_pk_fma_f32 v[78:79], v[24:25], v[94:95], v[28:29]
	v_pk_fma_f32 v[94:95], v[38:39], v[82:83], v[46:47]
	v_pk_mul_f32 v[82:83], v[88:89], v[114:115] op_sel_hi:[1,0]
	v_pk_mul_f32 v[88:89], v[90:91], v[114:115] op_sel_hi:[1,0]
	v_pk_fma_f32 v[66:67], v[2:3], v[74:75], v[6:7]
	v_pk_fma_f32 v[76:77], v[10:11], v[84:85], v[18:19]
	v_pk_fma_f32 v[74:75], v[8:9], v[80:81], v[16:17]
	v_pk_fma_f32 v[84:85], v[12:13], v[92:93], v[20:21]
	v_pk_fma_f32 v[80:81], v[26:27], v[70:71], v[30:31]
	v_pk_mul_f32 v[70:71], v[72:73], v[114:115] op_sel_hi:[1,0]
	v_pk_mul_f32 v[72:73], v[108:109], v[114:115] op_sel_hi:[1,0]
	v_pk_mul_f32 v[92:93], v[110:111], v[114:115] op_sel_hi:[1,0]
	v_pk_fma_f32 v[90:91], v[50:51], v[88:89], v[58:59]
	v_pk_fma_f32 v[88:89], v[48:49], v[82:83], v[56:57]
	v_pk_mul_f32 v[68:69], v[68:69], v[114:115] op_sel_hi:[1,0]
	v_pk_mul_f32 v[82:83], v[112:113], v[114:115] op_sel_hi:[1,0]
	v_pk_fma_f32 v[86:87], v[14:15], v[86:87], v[22:23]
	v_pk_fma_f32 v[72:73], v[34:35], v[72:73], v[42:43]
	v_pk_fma_f32 v[70:71], v[32:33], v[70:71], v[40:41]
	v_pk_fma_f32 v[92:93], v[36:37], v[92:93], v[44:45]
	v_pk_fma_f32 v[110:111], v[54:55], v[82:83], v[62:63]
	v_pk_fma_f32 v[108:109], v[52:53], v[68:69], v[60:61]
	global_store_dwordx4 v[96:97], v[64:67], off
	global_store_dwordx4 v[96:97], v[74:77], off offset:1024
	global_store_dwordx4 v[96:97], v[84:87], off offset:2048
	global_store_dwordx4 v[96:97], v[78:81], off offset:3072
	global_store_dwordx4 v[98:99], v[70:73], off
	global_store_dwordx4 v[98:99], v[92:95], off offset:1024
	global_store_dwordx4 v[98:99], v[88:91], off offset:2048
	global_store_dwordx4 v[98:99], v[108:111], off offset:3072
	v_lshl_add_u64 v[96:97], v[96:97], 0, s[4:5]
	s_waitcnt vmcnt(8)
	s_cmp_lt_i32 s2, 0x8000
	s_cbranch_scc1 .LBB0_1152
